# S5 pass 1/2: removed the workgroup barriers around per-wave-private LDS staging (first and last barrier of each item kept)
# speedup vs baseline: 1.0033x; 1.0033x over previous
; __device__ __forceinline__ void s5_bu16(const S5Frag& f, const bf16x8 uf, float* buL, int lane) {
;     const int jj = lane & 15, quad = lane >> 4;
; #pragma unroll
;     for (int nt = 0; nt < 4; ++nt) {
;         const f32x4 z = (f32x4){0.f, 0.f, 0.f, 0.f};
;         const f32x4 dre = __builtin_amdgcn_mfma_f32_16x16x32_bf16(uf, f.bfr[nt], z, 0, 0, 0);
;         const f32x4 dim = __builtin_amdgcn_mfma_f32_16x16x32_bf16(uf, f.bfr[nt + 4], z, 0, 0, 0);
; #pragma unroll
;         for (int r = 0; r < 4; ++r) *(f32x2*)(buL + ((4 * quad + r) * 64 + 16 * nt + jj) * 2) = (f32x2){dre[r], dim[r]};
;     }
; }
; __device__ __forceinline__ void s5_pass1_item(PP p, unsigned char* shm, int item, int l) {
;     ...
;     S5Frag f; s5_load_frags(bbL, f, lane);
;     f32x2 x = (f32x2){0.f, 0.f};
; #pragma unroll
;     for (int sc = 0; sc < 4; ++sc) {
;         s5_bu16(f, uf[sc], buL, lane);
;         __syncthreads();
; #pragma unroll
;         for (int t = 0; t < 16; ++t) s5_rec(q, *(const f32x2*)(buL + (t * 64 + lane) * 2), x);
;         __syncthreads();
;     }
.LBB0_552:
	s_or_b64 exec, exec, s[2:3]
	v_mul_f32_e32 v50, v59, v57
	v_lshl_add_u32 v52, v56, 13, 0
	s_waitcnt lgkmcnt(1)
	v_mfma_f32_16x16x32_bf16 v[56:59], v[46:49], v[26:29], 0
	v_and_b32_e32 v0, 0x600, v51
	v_lshl_add_u32 v51, v0, 2, v52
	v_lshlrev_b32_e32 v0, 3, v55
	v_mfma_f32_16x16x32_bf16 v[60:63], v[46:49], v[38:41], 0
	v_and_b32_e32 v55, 0x78, v0
	s_nop 2
	v_mov_b32_e32 v68, v56
	v_mov_b32_e32 v70, v58
	s_waitcnt lgkmcnt(0)
	v_mfma_f32_16x16x32_bf16 v[64:67], v[46:49], v[34:37], 0
	v_add_u32_e32 v74, v51, v55
	v_mov_b32_e32 v69, v60
	v_mov_b32_e32 v60, v57
	v_mov_b32_e32 v71, v62
	v_mov_b32_e32 v62, v59
	v_mfma_f32_16x16x32_bf16 v[56:59], v[46:49], v[14:17], 0
	v_or_b32_e32 v55, 0x180, v0
	v_add_u32_e32 v55, v51, v55
	v_add_u32_e32 v51, v52, v0
	v_mov_b32_e32 v52, v53
	v_mov_b32_e32 v73, v64
	s_nop 2
	v_mov_b32_e32 v72, v56
	v_add_u32_e32 v53, 0x1000, v74
	v_mov_b32_e32 v64, v57
	v_mov_b32_e32 v56, v58
	v_mov_b32_e32 v57, v66
	ds_write2_b64 v53, v[68:69], v[72:73] offset1:16
	ds_write2_b64 v53, v[70:71], v[56:57] offset0:128 offset1:144
	v_mov_b32_e32 v66, v59
	v_mfma_f32_16x16x32_bf16 v[56:59], v[46:49], v[6:9], 0
	v_readlane_b32 s2, v255, 9
	v_readlane_b32 s3, v255, 10
	s_mov_b32 s3, s19
	v_mfma_f32_16x16x32_bf16 v[68:71], v[46:49], v[18:21], 0
	s_mov_b32 s18, s2
	s_nop 2
	v_mov_b32_e32 v72, v56
	v_mov_b32_e32 v56, v58
	v_writelane_b32 v255, s18, 9
	s_nop 1
	v_writelane_b32 v255, s19, 10
	v_mov_b32_e32 v73, v68
	v_mov_b32_e32 v68, v57
	v_mov_b32_e32 v57, v70
	ds_write2_b64 v53, v[56:57], v[62:63] offset0:160 offset1:192
	v_mov_b32_e32 v70, v59
	v_mfma_f32_16x16x32_bf16 v[56:59], v[46:49], v[10:13], 0
	ds_write2_b64 v53, v[72:73], v[60:61] offset0:32 offset1:64
	ds_write2_b64 v53, v[64:65], v[68:69] offset0:80 offset1:96
	ds_write2_b64 v53, v[66:67], v[70:71] offset0:208 offset1:224
	v_mfma_f32_16x16x32_bf16 v[46:49], v[46:49], v[22:25], 0
	s_nop 3
	v_mov_b32_e32 v60, v56
	s_nop 2
	v_mov_b32_e32 v61, v46
	v_mov_b32_e32 v46, v57
	ds_write2st64_b64 v55, v[60:61], v[46:47] offset0:8 offset1:9
	v_mov_b32_e32 v46, v58
	v_mov_b32_e32 v47, v48
	v_mov_b32_e32 v48, v59
	ds_write2st64_b64 v55, v[46:47], v[48:49] offset0:10 offset1:11
	s_waitcnt lgkmcnt(0)
	ds_read2st64_b64 v[180:183], v51 offset0:8 offset1:9
	ds_read2st64_b64 v[184:187], v51 offset0:10 offset1:11
	ds_read2st64_b64 v[188:191], v51 offset0:12 offset1:13
	ds_read2st64_b64 v[192:195], v51 offset0:14 offset1:15
	ds_read2st64_b64 v[196:199], v51 offset0:16 offset1:17
	ds_read2st64_b64 v[200:203], v51 offset0:18 offset1:19
	ds_read2st64_b64 v[204:207], v51 offset0:20 offset1:21
	ds_read2st64_b64 v[208:211], v51 offset0:22 offset1:23
	v_pk_mul_f32 v[56:57], v[52:53], s[2:3] op_sel_hi:[0,1]
	v_pk_fma_f32 v[56:57], v[50:51], 0, v[56:57] op_sel_hi:[0,0,1]
	v_mfma_f32_16x16x32_bf16 v[60:63], v[42:45], v[34:37], 0
	s_lshl_b32 s2, s34, 10
	s_waitcnt lgkmcnt(7)
	v_pk_add_f32 v[46:47], v[56:57], v[180:181]
	s_lshl_b32 s3, s9, 5
	v_xor_b32_e32 v56, 0x80000000, v47
	v_mov_b32_e32 v57, v46
	v_pk_mul_f32 v[56:57], v[52:53], v[56:57] op_sel_hi:[0,1]
	v_pk_fma_f32 v[46:47], v[50:51], v[46:47], v[56:57] op_sel_hi:[0,1,1]
	v_pk_add_f32 v[56:57], v[182:183], v[46:47]
	v_xor_b32_e32 v58, 0x80000000, v57
	v_mov_b32_e32 v59, v56
	v_pk_mul_f32 v[58:59], v[52:53], v[58:59] op_sel_hi:[0,1]
	v_pk_fma_f32 v[56:57], v[50:51], v[56:57], v[58:59] op_sel_hi:[0,1,1]
	s_waitcnt lgkmcnt(6)
	v_pk_add_f32 v[46:47], v[184:185], v[56:57]
	v_mov_b32_e32 v71, v60
	v_xor_b32_e32 v56, 0x80000000, v47
	v_mov_b32_e32 v57, v46
	v_pk_mul_f32 v[56:57], v[52:53], v[56:57] op_sel_hi:[0,1]
	v_pk_fma_f32 v[46:47], v[50:51], v[46:47], v[56:57] op_sel_hi:[0,1,1]
	v_pk_add_f32 v[56:57], v[186:187], v[46:47]
	v_xor_b32_e32 v58, 0x80000000, v57
	v_mov_b32_e32 v59, v56
	v_pk_mul_f32 v[58:59], v[52:53], v[58:59] op_sel_hi:[0,1]
	v_pk_fma_f32 v[56:57], v[50:51], v[56:57], v[58:59] op_sel_hi:[0,1,1]
	s_waitcnt lgkmcnt(5)
	v_pk_add_f32 v[46:47], v[188:189], v[56:57]
	s_add_i32 s3, s3, s2
	v_xor_b32_e32 v56, 0x80000000, v47
	v_mov_b32_e32 v57, v46
	v_pk_mul_f32 v[56:57], v[52:53], v[56:57] op_sel_hi:[0,1]
	v_pk_fma_f32 v[46:47], v[50:51], v[46:47], v[56:57] op_sel_hi:[0,1,1]
	v_pk_add_f32 v[56:57], v[190:191], v[46:47]
	v_xor_b32_e32 v58, 0x80000000, v57
	v_mov_b32_e32 v59, v56
	v_pk_mul_f32 v[58:59], v[52:53], v[58:59] op_sel_hi:[0,1]
	v_pk_fma_f32 v[56:57], v[50:51], v[56:57], v[58:59] op_sel_hi:[0,1,1]
	s_waitcnt lgkmcnt(4)
	v_pk_add_f32 v[46:47], v[192:193], v[56:57]
	s_nop 0
	v_xor_b32_e32 v56, 0x80000000, v47
	v_mov_b32_e32 v57, v46
	v_pk_mul_f32 v[56:57], v[52:53], v[56:57] op_sel_hi:[0,1]
	v_pk_fma_f32 v[46:47], v[50:51], v[46:47], v[56:57] op_sel_hi:[0,1,1]
	v_pk_add_f32 v[56:57], v[194:195], v[46:47]
	v_xor_b32_e32 v58, 0x80000000, v57
	v_mov_b32_e32 v59, v56
	v_pk_mul_f32 v[58:59], v[52:53], v[58:59] op_sel_hi:[0,1]
	v_pk_fma_f32 v[56:57], v[50:51], v[56:57], v[58:59] op_sel_hi:[0,1,1]
	s_waitcnt lgkmcnt(3)
	v_pk_add_f32 v[46:47], v[196:197], v[56:57]
	s_nop 0
	v_xor_b32_e32 v56, 0x80000000, v47
	v_mov_b32_e32 v57, v46
	v_pk_mul_f32 v[56:57], v[52:53], v[56:57] op_sel_hi:[0,1]
	v_pk_fma_f32 v[46:47], v[50:51], v[46:47], v[56:57] op_sel_hi:[0,1,1]
	v_pk_add_f32 v[56:57], v[198:199], v[46:47]
	v_xor_b32_e32 v58, 0x80000000, v57
	v_mov_b32_e32 v59, v56
	v_pk_mul_f32 v[58:59], v[52:53], v[58:59] op_sel_hi:[0,1]
	v_pk_fma_f32 v[56:57], v[50:51], v[56:57], v[58:59] op_sel_hi:[0,1,1]
	s_waitcnt lgkmcnt(2)
; __device__ __forceinline__ void s5_bu16(const S5Frag& f, const bf16x8 uf, float* buL, int lane) {
;     const int jj = lane & 15, quad = lane >> 4;
; #pragma unroll
;     for (int nt = 0; nt < 4; ++nt) {
;         const f32x4 z = (f32x4){0.f, 0.f, 0.f, 0.f};
;         const f32x4 dre = __builtin_amdgcn_mfma_f32_16x16x32_bf16(uf, f.bfr[nt], z, 0, 0, 0);
;         const f32x4 dim = __builtin_amdgcn_mfma_f32_16x16x32_bf16(uf, f.bfr[nt + 4], z, 0, 0, 0);
; #pragma unroll
;         for (int r = 0; r < 4; ++r) *(f32x2*)(buL + ((4 * quad + r) * 64 + 16 * nt + jj) * 2) = (f32x2){dre[r], dim[r]};
;     }
; }
; __device__ __forceinline__ void s5_pass1_item(PP p, unsigned char* shm, int item, int l) {
;     ...
; #pragma unroll
;     for (int sc = 0; sc < 4; ++sc) {
;         s5_bu16(f, uf[sc], buL, lane);
;         __syncthreads();
; #pragma unroll
;         for (int t = 0; t < 16; ++t) s5_rec(q, *(const f32x2*)(buL + (t * 64 + lane) * 2), x);
;         __syncthreads();
;     }
	v_pk_add_f32 v[46:47], v[200:201], v[56:57]
	s_nop 0
	v_xor_b32_e32 v56, 0x80000000, v47
	v_mov_b32_e32 v57, v46
	v_pk_mul_f32 v[56:57], v[52:53], v[56:57] op_sel_hi:[0,1]
	v_pk_fma_f32 v[46:47], v[50:51], v[46:47], v[56:57] op_sel_hi:[0,1,1]
	v_pk_add_f32 v[56:57], v[202:203], v[46:47]
	v_xor_b32_e32 v58, 0x80000000, v57
	v_mov_b32_e32 v59, v56
	v_pk_mul_f32 v[58:59], v[52:53], v[58:59] op_sel_hi:[0,1]
	v_pk_fma_f32 v[56:57], v[50:51], v[56:57], v[58:59] op_sel_hi:[0,1,1]
	s_waitcnt lgkmcnt(1)
	v_pk_add_f32 v[46:47], v[204:205], v[56:57]
	s_nop 0
	v_xor_b32_e32 v56, 0x80000000, v47
	v_mov_b32_e32 v57, v46
	v_pk_mul_f32 v[56:57], v[52:53], v[56:57] op_sel_hi:[0,1]
	v_pk_fma_f32 v[46:47], v[50:51], v[46:47], v[56:57] op_sel_hi:[0,1,1]
	v_pk_add_f32 v[56:57], v[206:207], v[46:47]
	v_xor_b32_e32 v58, 0x80000000, v57
	v_mov_b32_e32 v59, v56
	v_pk_mul_f32 v[58:59], v[52:53], v[58:59] op_sel_hi:[0,1]
	v_pk_fma_f32 v[56:57], v[50:51], v[56:57], v[58:59] op_sel_hi:[0,1,1]
	s_waitcnt lgkmcnt(0)
	v_pk_add_f32 v[46:47], v[208:209], v[56:57]
	s_nop 0
	v_xor_b32_e32 v56, 0x80000000, v47
	v_mov_b32_e32 v57, v46
	v_pk_mul_f32 v[56:57], v[52:53], v[56:57] op_sel_hi:[0,1]
	v_pk_fma_f32 v[46:47], v[50:51], v[46:47], v[56:57] op_sel_hi:[0,1,1]
	v_pk_add_f32 v[68:69], v[210:211], v[46:47]
	v_mfma_f32_16x16x32_bf16 v[46:49], v[42:45], v[26:29], 0
	v_mfma_f32_16x16x32_bf16 v[56:59], v[42:45], v[38:41], 0
	s_nop 5
	v_mov_b32_e32 v64, v46
	s_nop 0
	v_mov_b32_e32 v65, v56
	v_mov_b32_e32 v56, v47
	v_mov_b32_e32 v66, v48
	v_mov_b32_e32 v67, v58
	v_mov_b32_e32 v58, v49
	v_mfma_f32_16x16x32_bf16 v[46:49], v[42:45], v[14:17], 0
	s_nop 7
	v_mov_b32_e32 v70, v46
	v_mov_b32_e32 v60, v47
	v_mov_b32_e32 v46, v48
	v_mov_b32_e32 v47, v62
	ds_write2_b64 v53, v[64:65], v[70:71] offset1:16
	ds_write2_b64 v53, v[66:67], v[46:47] offset0:128 offset1:144
	v_mov_b32_e32 v62, v49
	v_mfma_f32_16x16x32_bf16 v[46:49], v[42:45], v[6:9], 0
	v_mfma_f32_16x16x32_bf16 v[64:67], v[42:45], v[18:21], 0
	s_nop 6
	v_mov_b32_e32 v70, v46
	v_mov_b32_e32 v71, v64
	v_mov_b32_e32 v64, v47
	v_mov_b32_e32 v46, v48
	v_mov_b32_e32 v47, v66
	ds_write2_b64 v53, v[46:47], v[58:59] offset0:160 offset1:192
	v_mov_b32_e32 v66, v49
	v_mfma_f32_16x16x32_bf16 v[46:49], v[42:45], v[10:13], 0
	ds_write2_b64 v53, v[70:71], v[56:57] offset0:32 offset1:64
	ds_write2_b64 v53, v[60:61], v[64:65] offset0:80 offset1:96
	ds_write2_b64 v53, v[62:63], v[66:67] offset0:208 offset1:224
	v_mfma_f32_16x16x32_bf16 v[42:45], v[42:45], v[22:25], 0
	s_nop 3
	v_mov_b32_e32 v56, v46
	s_nop 2
	v_mov_b32_e32 v57, v42
	v_mov_b32_e32 v42, v47
	ds_write2st64_b64 v55, v[56:57], v[42:43] offset0:8 offset1:9
	v_mov_b32_e32 v42, v48
	v_mov_b32_e32 v43, v44
	v_mov_b32_e32 v44, v49
	ds_write2st64_b64 v55, v[42:43], v[44:45] offset0:10 offset1:11
	s_waitcnt lgkmcnt(0)
	ds_read2st64_b64 v[180:183], v51 offset0:8 offset1:9
	ds_read2st64_b64 v[184:187], v51 offset0:10 offset1:11
	ds_read2st64_b64 v[188:191], v51 offset0:12 offset1:13
	ds_read2st64_b64 v[192:195], v51 offset0:14 offset1:15
	ds_read2st64_b64 v[196:199], v51 offset0:16 offset1:17
	ds_read2st64_b64 v[200:203], v51 offset0:18 offset1:19
	ds_read2st64_b64 v[204:207], v51 offset0:20 offset1:21
	ds_read2st64_b64 v[208:211], v51 offset0:22 offset1:23
	v_xor_b32_e32 v46, 0x80000000, v69
	v_mov_b32_e32 v47, v68
	v_pk_mul_f32 v[46:47], v[52:53], v[46:47] op_sel_hi:[0,1]
	v_pk_fma_f32 v[46:47], v[50:51], v[68:69], v[46:47] op_sel_hi:[0,1,1]
	s_waitcnt lgkmcnt(7)
	v_pk_add_f32 v[42:43], v[180:181], v[46:47]
	v_mfma_f32_16x16x32_bf16 v[56:59], v[30:33], v[34:37], 0
	v_xor_b32_e32 v46, 0x80000000, v43
	v_mov_b32_e32 v47, v42
	v_pk_mul_f32 v[46:47], v[52:53], v[46:47] op_sel_hi:[0,1]
	v_pk_fma_f32 v[42:43], v[50:51], v[42:43], v[46:47] op_sel_hi:[0,1,1]
	v_pk_add_f32 v[46:47], v[182:183], v[42:43]
	v_xor_b32_e32 v48, 0x80000000, v47
	v_mov_b32_e32 v49, v46
	v_pk_mul_f32 v[48:49], v[52:53], v[48:49] op_sel_hi:[0,1]
	v_pk_fma_f32 v[46:47], v[50:51], v[46:47], v[48:49] op_sel_hi:[0,1,1]
	s_waitcnt lgkmcnt(6)
	v_pk_add_f32 v[42:43], v[184:185], v[46:47]
	v_mov_b32_e32 v67, v56
	v_xor_b32_e32 v46, 0x80000000, v43
	v_mov_b32_e32 v47, v42
	v_pk_mul_f32 v[46:47], v[52:53], v[46:47] op_sel_hi:[0,1]
	v_pk_fma_f32 v[42:43], v[50:51], v[42:43], v[46:47] op_sel_hi:[0,1,1]
	v_pk_add_f32 v[46:47], v[186:187], v[42:43]
	v_xor_b32_e32 v48, 0x80000000, v47
	v_mov_b32_e32 v49, v46
	v_pk_mul_f32 v[48:49], v[52:53], v[48:49] op_sel_hi:[0,1]
	v_pk_fma_f32 v[46:47], v[50:51], v[46:47], v[48:49] op_sel_hi:[0,1,1]
	s_waitcnt lgkmcnt(5)
	v_pk_add_f32 v[42:43], v[188:189], v[46:47]
	s_nop 0
	v_xor_b32_e32 v46, 0x80000000, v43
	v_mov_b32_e32 v47, v42
	v_pk_mul_f32 v[46:47], v[52:53], v[46:47] op_sel_hi:[0,1]
	v_pk_fma_f32 v[42:43], v[50:51], v[42:43], v[46:47] op_sel_hi:[0,1,1]
	v_pk_add_f32 v[46:47], v[190:191], v[42:43]
	v_xor_b32_e32 v48, 0x80000000, v47
	v_mov_b32_e32 v49, v46
	v_pk_mul_f32 v[48:49], v[52:53], v[48:49] op_sel_hi:[0,1]
	v_pk_fma_f32 v[46:47], v[50:51], v[46:47], v[48:49] op_sel_hi:[0,1,1]
	s_waitcnt lgkmcnt(4)
	v_pk_add_f32 v[42:43], v[192:193], v[46:47]
	s_nop 0
	v_xor_b32_e32 v46, 0x80000000, v43
	v_mov_b32_e32 v47, v42
	v_pk_mul_f32 v[46:47], v[52:53], v[46:47] op_sel_hi:[0,1]
	v_pk_fma_f32 v[42:43], v[50:51], v[42:43], v[46:47] op_sel_hi:[0,1,1]
	v_pk_add_f32 v[46:47], v[194:195], v[42:43]
	v_xor_b32_e32 v48, 0x80000000, v47
	v_mov_b32_e32 v49, v46
	v_pk_mul_f32 v[48:49], v[52:53], v[48:49] op_sel_hi:[0,1]
	v_pk_fma_f32 v[46:47], v[50:51], v[46:47], v[48:49] op_sel_hi:[0,1,1]
	s_waitcnt lgkmcnt(3)
; __device__ __forceinline__ void s5_bu16(const S5Frag& f, const bf16x8 uf, float* buL, int lane) {
;     const int jj = lane & 15, quad = lane >> 4;
; #pragma unroll
;     for (int nt = 0; nt < 4; ++nt) {
;         const f32x4 z = (f32x4){0.f, 0.f, 0.f, 0.f};
;         const f32x4 dre = __builtin_amdgcn_mfma_f32_16x16x32_bf16(uf, f.bfr[nt], z, 0, 0, 0);
;         const f32x4 dim = __builtin_amdgcn_mfma_f32_16x16x32_bf16(uf, f.bfr[nt + 4], z, 0, 0, 0);
; #pragma unroll
;         for (int r = 0; r < 4; ++r) *(f32x2*)(buL + ((4 * quad + r) * 64 + 16 * nt + jj) * 2) = (f32x2){dre[r], dim[r]};
;     }
; }
; __device__ __forceinline__ void s5_pass1_item(PP p, unsigned char* shm, int item, int l) {
;     ...
; #pragma unroll
;     for (int sc = 0; sc < 4; ++sc) {
;         s5_bu16(f, uf[sc], buL, lane);
;         __syncthreads();
; #pragma unroll
;         for (int t = 0; t < 16; ++t) s5_rec(q, *(const f32x2*)(buL + (t * 64 + lane) * 2), x);
;         __syncthreads();
;     }
	v_pk_add_f32 v[42:43], v[196:197], v[46:47]
	s_nop 0
	v_xor_b32_e32 v46, 0x80000000, v43
	v_mov_b32_e32 v47, v42
	v_pk_mul_f32 v[46:47], v[52:53], v[46:47] op_sel_hi:[0,1]
	v_pk_fma_f32 v[42:43], v[50:51], v[42:43], v[46:47] op_sel_hi:[0,1,1]
	v_pk_add_f32 v[46:47], v[198:199], v[42:43]
	v_xor_b32_e32 v48, 0x80000000, v47
	v_mov_b32_e32 v49, v46
	v_pk_mul_f32 v[48:49], v[52:53], v[48:49] op_sel_hi:[0,1]
	v_pk_fma_f32 v[46:47], v[50:51], v[46:47], v[48:49] op_sel_hi:[0,1,1]
	s_waitcnt lgkmcnt(2)
	v_pk_add_f32 v[42:43], v[200:201], v[46:47]
	s_nop 0
	v_xor_b32_e32 v46, 0x80000000, v43
	v_mov_b32_e32 v47, v42
	v_pk_mul_f32 v[46:47], v[52:53], v[46:47] op_sel_hi:[0,1]
	v_pk_fma_f32 v[42:43], v[50:51], v[42:43], v[46:47] op_sel_hi:[0,1,1]
	v_pk_add_f32 v[46:47], v[202:203], v[42:43]
	v_xor_b32_e32 v48, 0x80000000, v47
	v_mov_b32_e32 v49, v46
	v_pk_mul_f32 v[48:49], v[52:53], v[48:49] op_sel_hi:[0,1]
	v_pk_fma_f32 v[46:47], v[50:51], v[46:47], v[48:49] op_sel_hi:[0,1,1]
	s_waitcnt lgkmcnt(1)
	v_pk_add_f32 v[42:43], v[204:205], v[46:47]
	s_nop 0
	v_xor_b32_e32 v46, 0x80000000, v43
	v_mov_b32_e32 v47, v42
	v_pk_mul_f32 v[46:47], v[52:53], v[46:47] op_sel_hi:[0,1]
	v_pk_fma_f32 v[42:43], v[50:51], v[42:43], v[46:47] op_sel_hi:[0,1,1]
	v_pk_add_f32 v[46:47], v[206:207], v[42:43]
	v_xor_b32_e32 v48, 0x80000000, v47
	v_mov_b32_e32 v49, v46
	v_pk_mul_f32 v[48:49], v[52:53], v[48:49] op_sel_hi:[0,1]
	v_pk_fma_f32 v[46:47], v[50:51], v[46:47], v[48:49] op_sel_hi:[0,1,1]
	s_waitcnt lgkmcnt(0)
	v_pk_add_f32 v[42:43], v[208:209], v[46:47]
	s_nop 0
	v_xor_b32_e32 v46, 0x80000000, v43
	v_mov_b32_e32 v47, v42
	v_pk_mul_f32 v[46:47], v[52:53], v[46:47] op_sel_hi:[0,1]
	v_pk_fma_f32 v[42:43], v[50:51], v[42:43], v[46:47] op_sel_hi:[0,1,1]
	v_pk_add_f32 v[64:65], v[210:211], v[42:43]
	v_mfma_f32_16x16x32_bf16 v[42:45], v[30:33], v[26:29], 0
	v_mfma_f32_16x16x32_bf16 v[46:49], v[30:33], v[38:41], 0
	v_mfma_f32_16x16x32_bf16 v[26:29], v[2:5], v[26:29], 0
	s_nop 4
	v_mov_b32_e32 v60, v42
	s_nop 0
	v_mov_b32_e32 v61, v46
	v_mov_b32_e32 v46, v43
	v_mov_b32_e32 v62, v44
	v_mov_b32_e32 v63, v48
	v_mov_b32_e32 v48, v45
	v_mfma_f32_16x16x32_bf16 v[42:45], v[30:33], v[14:17], 0
	v_mfma_f32_16x16x32_bf16 v[14:17], v[2:5], v[14:17], 0
	s_nop 6
	v_mov_b32_e32 v66, v42
	v_mov_b32_e32 v56, v43
	v_mov_b32_e32 v42, v44
	v_mov_b32_e32 v43, v58
	ds_write2_b64 v53, v[60:61], v[66:67] offset1:16
	ds_write2_b64 v53, v[62:63], v[42:43] offset0:128 offset1:144
	v_mov_b32_e32 v58, v45
	v_mfma_f32_16x16x32_bf16 v[42:45], v[30:33], v[6:9], 0
	v_mfma_f32_16x16x32_bf16 v[60:63], v[30:33], v[18:21], 0
	v_mfma_f32_16x16x32_bf16 v[6:9], v[2:5], v[6:9], 0
	s_nop 5
	v_mov_b32_e32 v66, v42
	v_mov_b32_e32 v67, v60
	v_mov_b32_e32 v60, v43
	v_mov_b32_e32 v42, v44
	v_mov_b32_e32 v43, v62
	ds_write2_b64 v53, v[42:43], v[48:49] offset0:160 offset1:192
	v_mov_b32_e32 v62, v45
	v_mfma_f32_16x16x32_bf16 v[42:45], v[30:33], v[10:13], 0
	ds_write2_b64 v53, v[66:67], v[46:47] offset0:32 offset1:64
	ds_write2_b64 v53, v[56:57], v[60:61] offset0:80 offset1:96
	ds_write2_b64 v53, v[58:59], v[62:63] offset0:208 offset1:224
	v_mfma_f32_16x16x32_bf16 v[30:33], v[30:33], v[22:25], 0
	s_nop 3
	v_mov_b32_e32 v46, v42
	s_nop 2
	v_mov_b32_e32 v47, v30
	v_mov_b32_e32 v30, v43
	ds_write2st64_b64 v55, v[46:47], v[30:31] offset0:8 offset1:9
	v_mov_b32_e32 v30, v44
	v_mov_b32_e32 v31, v32
	v_mov_b32_e32 v32, v45
	ds_write2st64_b64 v55, v[30:31], v[32:33] offset0:10 offset1:11
	s_waitcnt lgkmcnt(0)
	ds_read2st64_b64 v[180:183], v51 offset0:8 offset1:9
	ds_read2st64_b64 v[184:187], v51 offset0:10 offset1:11
	ds_read2st64_b64 v[188:191], v51 offset0:12 offset1:13
	ds_read2st64_b64 v[192:195], v51 offset0:14 offset1:15
	ds_read2st64_b64 v[196:199], v51 offset0:16 offset1:17
	ds_read2st64_b64 v[200:203], v51 offset0:18 offset1:19
	ds_read2st64_b64 v[204:207], v51 offset0:20 offset1:21
	ds_read2st64_b64 v[208:211], v51 offset0:22 offset1:23
	v_xor_b32_e32 v42, 0x80000000, v65
	v_mov_b32_e32 v43, v64
	v_pk_mul_f32 v[42:43], v[52:53], v[42:43] op_sel_hi:[0,1]
	v_pk_fma_f32 v[42:43], v[50:51], v[64:65], v[42:43] op_sel_hi:[0,1,1]
	s_waitcnt lgkmcnt(7)
	v_pk_add_f32 v[30:31], v[180:181], v[42:43]
	s_nop 0
	v_xor_b32_e32 v42, 0x80000000, v31
	v_mov_b32_e32 v43, v30
	v_pk_mul_f32 v[42:43], v[52:53], v[42:43] op_sel_hi:[0,1]
	v_pk_fma_f32 v[30:31], v[50:51], v[30:31], v[42:43] op_sel_hi:[0,1,1]
	v_pk_add_f32 v[42:43], v[182:183], v[30:31]
	v_xor_b32_e32 v44, 0x80000000, v43
	v_mov_b32_e32 v45, v42
	v_pk_mul_f32 v[44:45], v[52:53], v[44:45] op_sel_hi:[0,1]
	v_pk_fma_f32 v[42:43], v[50:51], v[42:43], v[44:45] op_sel_hi:[0,1,1]
	s_waitcnt lgkmcnt(6)
	v_pk_add_f32 v[30:31], v[184:185], v[42:43]
	s_nop 0
	v_xor_b32_e32 v42, 0x80000000, v31
	v_mov_b32_e32 v43, v30
	v_pk_mul_f32 v[42:43], v[52:53], v[42:43] op_sel_hi:[0,1]
	v_pk_fma_f32 v[30:31], v[50:51], v[30:31], v[42:43] op_sel_hi:[0,1,1]
	v_pk_add_f32 v[42:43], v[186:187], v[30:31]
	v_xor_b32_e32 v44, 0x80000000, v43
	v_mov_b32_e32 v45, v42
	v_pk_mul_f32 v[44:45], v[52:53], v[44:45] op_sel_hi:[0,1]
	v_pk_fma_f32 v[42:43], v[50:51], v[42:43], v[44:45] op_sel_hi:[0,1,1]
	s_waitcnt lgkmcnt(5)
	v_pk_add_f32 v[30:31], v[188:189], v[42:43]
	s_nop 0
	v_xor_b32_e32 v42, 0x80000000, v31
	v_mov_b32_e32 v43, v30
	v_pk_mul_f32 v[42:43], v[52:53], v[42:43] op_sel_hi:[0,1]
	v_pk_fma_f32 v[30:31], v[50:51], v[30:31], v[42:43] op_sel_hi:[0,1,1]
	v_pk_add_f32 v[42:43], v[190:191], v[30:31]
	v_xor_b32_e32 v44, 0x80000000, v43
	v_mov_b32_e32 v45, v42
	v_pk_mul_f32 v[44:45], v[52:53], v[44:45] op_sel_hi:[0,1]
	v_pk_fma_f32 v[42:43], v[50:51], v[42:43], v[44:45] op_sel_hi:[0,1,1]
	s_waitcnt lgkmcnt(4)
; __device__ __forceinline__ void s5_bu16(const S5Frag& f, const bf16x8 uf, float* buL, int lane) {
;     const int jj = lane & 15, quad = lane >> 4;
; #pragma unroll
;     for (int nt = 0; nt < 4; ++nt) {
;         const f32x4 z = (f32x4){0.f, 0.f, 0.f, 0.f};
;         const f32x4 dre = __builtin_amdgcn_mfma_f32_16x16x32_bf16(uf, f.bfr[nt], z, 0, 0, 0);
;         const f32x4 dim = __builtin_amdgcn_mfma_f32_16x16x32_bf16(uf, f.bfr[nt + 4], z, 0, 0, 0);
; #pragma unroll
;         for (int r = 0; r < 4; ++r) *(f32x2*)(buL + ((4 * quad + r) * 64 + 16 * nt + jj) * 2) = (f32x2){dre[r], dim[r]};
;     }
; }
; __device__ __forceinline__ void s5_pass1_item(PP p, unsigned char* shm, int item, int l) {
;     ...
; #pragma unroll
;     for (int sc = 0; sc < 4; ++sc) {
;         s5_bu16(f, uf[sc], buL, lane);
;         __syncthreads();
; #pragma unroll
;         for (int t = 0; t < 16; ++t) s5_rec(q, *(const f32x2*)(buL + (t * 64 + lane) * 2), x);
;         __syncthreads();
;     }
	v_pk_add_f32 v[30:31], v[192:193], v[42:43]
	s_nop 0
	v_xor_b32_e32 v42, 0x80000000, v31
	v_mov_b32_e32 v43, v30
	v_pk_mul_f32 v[42:43], v[52:53], v[42:43] op_sel_hi:[0,1]
	v_pk_fma_f32 v[30:31], v[50:51], v[30:31], v[42:43] op_sel_hi:[0,1,1]
	v_pk_add_f32 v[42:43], v[194:195], v[30:31]
	v_xor_b32_e32 v44, 0x80000000, v43
	v_mov_b32_e32 v45, v42
	v_pk_mul_f32 v[44:45], v[52:53], v[44:45] op_sel_hi:[0,1]
	v_pk_fma_f32 v[42:43], v[50:51], v[42:43], v[44:45] op_sel_hi:[0,1,1]
	s_waitcnt lgkmcnt(3)
	v_pk_add_f32 v[30:31], v[196:197], v[42:43]
	s_nop 0
	v_xor_b32_e32 v42, 0x80000000, v31
	v_mov_b32_e32 v43, v30
	v_pk_mul_f32 v[42:43], v[52:53], v[42:43] op_sel_hi:[0,1]
	v_pk_fma_f32 v[30:31], v[50:51], v[30:31], v[42:43] op_sel_hi:[0,1,1]
	v_pk_add_f32 v[42:43], v[198:199], v[30:31]
	v_xor_b32_e32 v44, 0x80000000, v43
	v_mov_b32_e32 v45, v42
	v_pk_mul_f32 v[44:45], v[52:53], v[44:45] op_sel_hi:[0,1]
	v_pk_fma_f32 v[42:43], v[50:51], v[42:43], v[44:45] op_sel_hi:[0,1,1]
	s_waitcnt lgkmcnt(2)
	v_pk_add_f32 v[30:31], v[200:201], v[42:43]
	s_nop 0
	v_xor_b32_e32 v42, 0x80000000, v31
	v_mov_b32_e32 v43, v30
	v_pk_mul_f32 v[42:43], v[52:53], v[42:43] op_sel_hi:[0,1]
	v_pk_fma_f32 v[30:31], v[50:51], v[30:31], v[42:43] op_sel_hi:[0,1,1]
	v_pk_add_f32 v[42:43], v[202:203], v[30:31]
	v_xor_b32_e32 v44, 0x80000000, v43
	v_mov_b32_e32 v45, v42
	v_pk_mul_f32 v[44:45], v[52:53], v[44:45] op_sel_hi:[0,1]
	v_pk_fma_f32 v[42:43], v[50:51], v[42:43], v[44:45] op_sel_hi:[0,1,1]
	s_waitcnt lgkmcnt(1)
	v_pk_add_f32 v[30:31], v[204:205], v[42:43]
	s_nop 0
	v_xor_b32_e32 v42, 0x80000000, v31
	v_mov_b32_e32 v43, v30
	v_pk_mul_f32 v[42:43], v[52:53], v[42:43] op_sel_hi:[0,1]
	v_pk_fma_f32 v[30:31], v[50:51], v[30:31], v[42:43] op_sel_hi:[0,1,1]
	v_pk_add_f32 v[42:43], v[206:207], v[30:31]
	v_xor_b32_e32 v44, 0x80000000, v43
	v_mov_b32_e32 v45, v42
	v_pk_mul_f32 v[44:45], v[52:53], v[44:45] op_sel_hi:[0,1]
	v_pk_fma_f32 v[42:43], v[50:51], v[42:43], v[44:45] op_sel_hi:[0,1,1]
	s_waitcnt lgkmcnt(0)
	v_pk_add_f32 v[30:31], v[208:209], v[42:43]
	s_nop 0
	v_xor_b32_e32 v42, 0x80000000, v31
	v_mov_b32_e32 v43, v30
	v_pk_mul_f32 v[42:43], v[52:53], v[42:43] op_sel_hi:[0,1]
	v_pk_fma_f32 v[30:31], v[50:51], v[30:31], v[42:43] op_sel_hi:[0,1,1]
	v_pk_add_f32 v[42:43], v[210:211], v[30:31]
	v_mfma_f32_16x16x32_bf16 v[30:33], v[2:5], v[38:41], 0
	v_mov_b32_e32 v38, v26
	v_mov_b32_e32 v40, v28
	s_nop 4
	v_mov_b32_e32 v39, v30
	v_mov_b32_e32 v30, v27
	v_mov_b32_e32 v41, v32
	v_mov_b32_e32 v32, v29
	v_mfma_f32_16x16x32_bf16 v[26:29], v[2:5], v[34:37], 0
	v_mov_b32_e32 v34, v14
	v_mov_b32_e32 v14, v16
	s_nop 5
	v_mov_b32_e32 v35, v26
	v_mov_b32_e32 v26, v15
	v_mov_b32_e32 v15, v28
	ds_write2_b64 v53, v[40:41], v[14:15] offset0:128 offset1:144
	v_mov_b32_e32 v28, v17
	v_mfma_f32_16x16x32_bf16 v[14:17], v[2:5], v[18:21], 0
	v_mov_b32_e32 v18, v6
	v_mov_b32_e32 v6, v8
	ds_write2_b64 v53, v[38:39], v[34:35] offset1:16
	s_nop 4
	v_mov_b32_e32 v19, v14
	v_mov_b32_e32 v14, v7
	v_mov_b32_e32 v7, v16
	ds_write2_b64 v53, v[6:7], v[32:33] offset0:160 offset1:192
	v_mov_b32_e32 v16, v9
	v_mfma_f32_16x16x32_bf16 v[6:9], v[2:5], v[10:13], 0
	ds_write2_b64 v53, v[18:19], v[30:31] offset0:32 offset1:64
	ds_write2_b64 v53, v[26:27], v[14:15] offset0:80 offset1:96
	ds_write2_b64 v53, v[28:29], v[16:17] offset0:208 offset1:224
	v_mfma_f32_16x16x32_bf16 v[2:5], v[2:5], v[22:25], 0
	s_nop 3
	v_mov_b32_e32 v10, v6
	s_nop 2
	v_mov_b32_e32 v11, v2
	v_mov_b32_e32 v2, v7
	ds_write2st64_b64 v55, v[10:11], v[2:3] offset0:8 offset1:9
	v_mov_b32_e32 v2, v8
	v_mov_b32_e32 v3, v4
	v_mov_b32_e32 v4, v9
	ds_write2st64_b64 v55, v[2:3], v[4:5] offset0:10 offset1:11
	s_waitcnt lgkmcnt(0)
	ds_read2st64_b64 v[180:183], v51 offset0:8 offset1:9
	ds_read2st64_b64 v[184:187], v51 offset0:10 offset1:11
	ds_read2st64_b64 v[188:191], v51 offset0:12 offset1:13
	ds_read2st64_b64 v[192:195], v51 offset0:14 offset1:15
	ds_read2st64_b64 v[196:199], v51 offset0:16 offset1:17
	ds_read2st64_b64 v[200:203], v51 offset0:18 offset1:19
	ds_read2st64_b64 v[204:207], v51 offset0:20 offset1:21
	ds_read2st64_b64 v[208:211], v51 offset0:22 offset1:23
	v_xor_b32_e32 v6, 0x80000000, v43
	v_mov_b32_e32 v7, v42
	v_pk_mul_f32 v[6:7], v[52:53], v[6:7] op_sel_hi:[0,1]
	v_pk_fma_f32 v[6:7], v[50:51], v[42:43], v[6:7] op_sel_hi:[0,1,1]
	s_waitcnt lgkmcnt(7)
; __device__ __forceinline__ void s5_bu16(const S5Frag& f, const bf16x8 uf, float* buL, int lane) {
;     const int jj = lane & 15, quad = lane >> 4;
; #pragma unroll
;     for (int nt = 0; nt < 4; ++nt) {
;         const f32x4 z = (f32x4){0.f, 0.f, 0.f, 0.f};
;         const f32x4 dre = __builtin_amdgcn_mfma_f32_16x16x32_bf16(uf, f.bfr[nt], z, 0, 0, 0);
;         const f32x4 dim = __builtin_amdgcn_mfma_f32_16x16x32_bf16(uf, f.bfr[nt + 4], z, 0, 0, 0);
; #pragma unroll
;         for (int r = 0; r < 4; ++r) *(f32x2*)(buL + ((4 * quad + r) * 64 + 16 * nt + jj) * 2) = (f32x2){dre[r], dim[r]};
;     }
; }
; __device__ __forceinline__ void s5_pass1_item(PP p, unsigned char* shm, int item, int l) {
;     ...
; #pragma unroll
;     for (int sc = 0; sc < 4; ++sc) {
;         s5_bu16(f, uf[sc], buL, lane);
;         __syncthreads();
; #pragma unroll
;         for (int t = 0; t < 16; ++t) s5_rec(q, *(const f32x2*)(buL + (t * 64 + lane) * 2), x);
;         __syncthreads();
;     }
;     *(f32x2*)((float*)(p->ws + WS_CARRY) + ((size_t)((b * 32 + g) * 32 + j) * 64 + lane) * 2) = x;
	v_pk_add_f32 v[2:3], v[180:181], v[6:7]
	s_nop 0
	v_xor_b32_e32 v6, 0x80000000, v3
	v_mov_b32_e32 v7, v2
	v_pk_mul_f32 v[6:7], v[52:53], v[6:7] op_sel_hi:[0,1]
	v_pk_fma_f32 v[2:3], v[50:51], v[2:3], v[6:7] op_sel_hi:[0,1,1]
	v_pk_add_f32 v[6:7], v[182:183], v[2:3]
	v_xor_b32_e32 v8, 0x80000000, v7
	v_mov_b32_e32 v9, v6
	v_pk_mul_f32 v[8:9], v[52:53], v[8:9] op_sel_hi:[0,1]
	v_pk_fma_f32 v[6:7], v[50:51], v[6:7], v[8:9] op_sel_hi:[0,1,1]
	s_waitcnt lgkmcnt(6)
	v_pk_add_f32 v[2:3], v[184:185], v[6:7]
	s_nop 0
	v_xor_b32_e32 v6, 0x80000000, v3
	v_mov_b32_e32 v7, v2
	v_pk_mul_f32 v[6:7], v[52:53], v[6:7] op_sel_hi:[0,1]
	v_pk_fma_f32 v[2:3], v[50:51], v[2:3], v[6:7] op_sel_hi:[0,1,1]
	v_pk_add_f32 v[6:7], v[186:187], v[2:3]
	v_xor_b32_e32 v8, 0x80000000, v7
	v_mov_b32_e32 v9, v6
	v_pk_mul_f32 v[8:9], v[52:53], v[8:9] op_sel_hi:[0,1]
	v_pk_fma_f32 v[6:7], v[50:51], v[6:7], v[8:9] op_sel_hi:[0,1,1]
	s_waitcnt lgkmcnt(5)
	v_pk_add_f32 v[2:3], v[188:189], v[6:7]
	s_nop 0
	v_xor_b32_e32 v6, 0x80000000, v3
	v_mov_b32_e32 v7, v2
	v_pk_mul_f32 v[6:7], v[52:53], v[6:7] op_sel_hi:[0,1]
	v_pk_fma_f32 v[2:3], v[50:51], v[2:3], v[6:7] op_sel_hi:[0,1,1]
	v_pk_add_f32 v[6:7], v[190:191], v[2:3]
	v_xor_b32_e32 v8, 0x80000000, v7
	v_mov_b32_e32 v9, v6
	v_pk_mul_f32 v[8:9], v[52:53], v[8:9] op_sel_hi:[0,1]
	v_pk_fma_f32 v[6:7], v[50:51], v[6:7], v[8:9] op_sel_hi:[0,1,1]
	s_waitcnt lgkmcnt(4)
	v_pk_add_f32 v[2:3], v[192:193], v[6:7]
	s_nop 0
	v_xor_b32_e32 v6, 0x80000000, v3
	v_mov_b32_e32 v7, v2
	v_pk_mul_f32 v[6:7], v[52:53], v[6:7] op_sel_hi:[0,1]
	v_pk_fma_f32 v[2:3], v[50:51], v[2:3], v[6:7] op_sel_hi:[0,1,1]
	v_pk_add_f32 v[6:7], v[194:195], v[2:3]
	v_xor_b32_e32 v8, 0x80000000, v7
	v_mov_b32_e32 v9, v6
	v_pk_mul_f32 v[8:9], v[52:53], v[8:9] op_sel_hi:[0,1]
	v_pk_fma_f32 v[6:7], v[50:51], v[6:7], v[8:9] op_sel_hi:[0,1,1]
	s_waitcnt lgkmcnt(3)
	v_pk_add_f32 v[2:3], v[196:197], v[6:7]
	s_nop 0
	v_xor_b32_e32 v6, 0x80000000, v3
	v_mov_b32_e32 v7, v2
	v_pk_mul_f32 v[6:7], v[52:53], v[6:7] op_sel_hi:[0,1]
	v_pk_fma_f32 v[2:3], v[50:51], v[2:3], v[6:7] op_sel_hi:[0,1,1]
	v_pk_add_f32 v[6:7], v[198:199], v[2:3]
	v_xor_b32_e32 v8, 0x80000000, v7
	v_mov_b32_e32 v9, v6
	v_pk_mul_f32 v[8:9], v[52:53], v[8:9] op_sel_hi:[0,1]
	v_pk_fma_f32 v[6:7], v[50:51], v[6:7], v[8:9] op_sel_hi:[0,1,1]
	s_waitcnt lgkmcnt(2)
	v_pk_add_f32 v[2:3], v[200:201], v[6:7]
	s_nop 0
	v_xor_b32_e32 v6, 0x80000000, v3
	v_mov_b32_e32 v7, v2
	v_pk_mul_f32 v[6:7], v[52:53], v[6:7] op_sel_hi:[0,1]
	v_pk_fma_f32 v[2:3], v[50:51], v[2:3], v[6:7] op_sel_hi:[0,1,1]
	v_pk_add_f32 v[6:7], v[202:203], v[2:3]
	v_xor_b32_e32 v8, 0x80000000, v7
	v_mov_b32_e32 v9, v6
	v_pk_mul_f32 v[8:9], v[52:53], v[8:9] op_sel_hi:[0,1]
	v_pk_fma_f32 v[6:7], v[50:51], v[6:7], v[8:9] op_sel_hi:[0,1,1]
	s_waitcnt lgkmcnt(1)
	v_pk_add_f32 v[2:3], v[204:205], v[6:7]
	s_nop 0
	v_xor_b32_e32 v6, 0x80000000, v3
	v_mov_b32_e32 v7, v2
	v_pk_mul_f32 v[6:7], v[52:53], v[6:7] op_sel_hi:[0,1]
	v_pk_fma_f32 v[2:3], v[50:51], v[2:3], v[6:7] op_sel_hi:[0,1,1]
	v_pk_add_f32 v[6:7], v[206:207], v[2:3]
	v_xor_b32_e32 v8, 0x80000000, v7
	v_mov_b32_e32 v9, v6
	v_pk_mul_f32 v[8:9], v[52:53], v[8:9] op_sel_hi:[0,1]
	v_pk_fma_f32 v[6:7], v[50:51], v[6:7], v[8:9] op_sel_hi:[0,1,1]
	s_waitcnt lgkmcnt(0)
	v_pk_add_f32 v[2:3], v[208:209], v[6:7]
	s_nop 0
	v_xor_b32_e32 v6, 0x80000000, v3
	v_mov_b32_e32 v7, v2
	v_pk_mul_f32 v[6:7], v[52:53], v[6:7] op_sel_hi:[0,1]
	v_pk_fma_f32 v[2:3], v[50:51], v[2:3], v[6:7] op_sel_hi:[0,1,1]
	v_pk_add_f32 v[2:3], v[210:211], v[2:3]
	v_add_u32_e32 v4, s3, v54
	v_ashrrev_i32_e32 v5, 31, v4
	v_lshlrev_b64 v[4:5], 9, v[4:5]
	v_lshl_add_u64 v[4:5], s[12:13], 0, v[4:5]
	v_lshl_add_u64 v[4:5], v[4:5], 0, v[0:1]
	v_add_co_u32_e32 v4, vcc, 0x31ac0000, v4
	s_barrier
	s_nop 0
	v_addc_co_u32_e32 v5, vcc, 0, v5, vcc
	global_store_dwordx2 v[4:5], v[2:3], off

; __device__ __forceinline__ void s5_pass2_item(PP p, unsigned char* shm, int item, int l) {
;     ...
;     float cmr[32];
;     { const float* src = ((quad < 2) ? p->in[11] : p->in[12]) + ((size_t)(l * 32 + g) * 16 + cc) * 64 + (quad & 1) * 32;
;       const float sgn = (quad < 2) ? 1.0f : -1.0f;
; #pragma unroll
;       for (int i = 0; i < 8; ++i) { const f32x4 v = *(const f32x4*)(src + 4 * i); cmr[4 * i] = v[0] * sgn; cmr[4 * i + 1] = v[1] * sgn; cmr[4 * i + 2] = v[2] * sgn; cmr[4 * i + 3] = v[3] * sgn; } }
;     S5Lane q; s5_lane_params(p, l, g, lane, q);
;     const size_t row0 = (size_t)b * SEQ + j * 64;
;     bf16x8 uf[4];
; #pragma unroll
;     for (int sc = 0; sc < 4; ++sc) uf[sc] = s5_ufrag(proj, row0 + sc * 16, g, lane);
;     s5_write_bbl(q, bbL, lane);
;     float pr = q.ar, pi = q.ai;
; #pragma unroll
;     for (int s = 0; s < 6; ++s) { const float nr = pr * pr - pi * pi, ni = 2.f * pr * pi; pr = nr; pi = ni; }
;     f32x2 x = (f32x2){0.f, 0.f};
;     const f32x2* carry = (const f32x2*)((const float*)(p->ws + WS_CARRY) + ((size_t)((b * 32 + g) * 32) * 64 + lane) * 2);
;     for (int i0 = 0; i0 < j; i0 += 8) {
;         f32x2 sv[8];
; #pragma unroll
;         for (int e = 0; e < 8; ++e) sv[e] = (i0 + e < j) ? carry[(size_t)(i0 + e) * 64] : (f32x2){0.f, 0.f};
; #pragma unroll
;         for (int e = 0; e < 8; ++e) if (i0 + e < j) { const f32x2 rot = (f32x2){-x.y, x.x}; x = (x * pr + rot * pi) + sv[e]; }
;     }
;     __syncthreads();
;     S5Frag f; s5_load_frags(bbL, f, lane);
;     const float dsk = p->in[13][(size_t)l * 512 + g * 16 + cc];
;     bf16_t* Gout = (bf16_t*)(p->ws + WS_GPH);
;     for (int sc = 0; sc < 4; ++sc) {
;         s5_bu16(f, uf[sc], buL, lane);
;         __syncthreads();
; #pragma unroll
;         for (int t = 0; t < 16; ++t) { s5_rec(q, *(const f32x2*)(buL + (t * 64 + lane) * 2), x); xs[t * 132 + lane] = x.x; xs[t * 132 + 64 + lane] = x.y; }
.LBB0_679:
	s_or_b64 exec, exec, s[2:3]
	s_movk_i32 s2, 0x2100
	v_mul_lo_u32 v0, v93, s2
	s_add_i32 s2, 0, 0x11000
	v_add_u32_e32 v102, s2, v0
	s_load_dwordx2 s[2:3], s[12:13], 0x68
	v_lshl_add_u32 v0, v93, 13, 0
	v_mul_f32_e32 v77, v77, v97
	v_mul_f32_e32 v76, v76, v97
	v_mul_f32_e32 v75, v75, v97
	s_waitcnt lgkmcnt(0)
	s_add_u32 s12, s2, s18
	s_addc_u32 s13, s3, 0
	s_lshl_b64 s[2:3], s[34:35], 2
	s_add_u32 s2, s12, s2
	v_mul_f32_e32 v74, v74, v97
	v_mul_f32_e32 v73, v73, v97
	v_mul_f32_e32 v72, v72, v97
	v_mul_f32_e32 v71, v71, v97
	v_mul_f32_e32 v70, v70, v97
	v_mul_f32_e32 v69, v69, v97
	v_mul_f32_e32 v68, v68, v97
	v_mul_f32_e32 v67, v67, v97
	v_mul_f32_e32 v66, v66, v97
	v_mul_f32_e32 v65, v65, v97
	v_mul_f32_e32 v64, v64, v97
	v_mul_f32_e32 v63, v63, v97
	v_mul_f32_e32 v62, v62, v97
	v_mul_f32_e32 v61, v61, v97
	v_mul_f32_e32 v60, v60, v97
	v_mul_f32_e32 v59, v59, v97
	v_mul_f32_e32 v58, v58, v97
	v_mul_f32_e32 v57, v57, v97
	v_mul_f32_e32 v56, v56, v97
	v_mul_f32_e32 v55, v55, v97
	v_mul_f32_e32 v85, v54, v97
	v_mul_f32_e32 v88, v53, v97
	v_mul_f32_e32 v91, v52, v97
	v_mul_f32_e32 v92, v51, v97
	v_mul_f32_e32 v93, v50, v97
	v_mul_f32_e32 v94, v49, v97
	v_mul_f32_e32 v95, v48, v97
	v_mul_f32_e32 v96, v47, v97
	v_mul_f32_e32 v97, v46, v97
	s_addc_u32 s3, s13, s3
	v_lshlrev_b32_e32 v46, 2, v100
	global_load_dword v54, v46, s[2:3]
	v_and_b32_e32 v46, 0x600, v99
	v_lshl_add_u32 v46, v46, 2, v0
	v_and_b32_e32 v47, 0x78, v90
	v_add_u32_e32 v108, v46, v47
	v_or_b32_e32 v47, 0x180, v90
	v_add_u32_e32 v99, v46, v47
	v_mul_u32_u24_e32 v46, 0x210, v100
	v_lshlrev_b32_e32 v47, 2, v101
	v_add_u32_e32 v90, v0, v90
	v_mov_b32_e32 v0, v89
	v_lshl_add_u32 v98, v98, 2, v102
	v_add3_u32 v89, v102, v46, v47
	v_or_b32_e32 v50, s34, v100
	v_mfma_f32_16x16x32_bf16 v[46:49], v[78:81], v[26:29], 0
	v_add_u32_e32 v108, 0x1000, v108
	v_lshl_or_b32 v82, v109, 2, v82
	v_mov_b32_e32 v51, s35
	v_mfma_f32_16x16x32_bf16 v[100:103], v[78:81], v[34:37], 0
	s_add_u32 s28, s28, 0x21600000
	s_nop 2
	v_mov_b32_e32 v52, v46
	v_mov_b32_e32 v110, v48
	v_mfma_f32_16x16x32_bf16 v[104:107], v[78:81], v[30:33], 0
	s_addc_u32 s29, s29, 0
	v_mov_b32_e32 v53, v100
	v_mov_b32_e32 v100, v47
	v_mov_b32_e32 v111, v102
	v_mov_b32_e32 v102, v49
	v_mfma_f32_16x16x32_bf16 v[46:49], v[78:81], v[22:25], 0
	s_nop 1
	v_mov_b32_e32 v113, v104
	s_xor_b32 s14, s14, 3
	s_add_i32 s14, s14, s66
	s_cmpk_gt_i32 s14, 0x1ff
	s_nop 2
	v_mov_b32_e32 v112, v46
	v_mov_b32_e32 v104, v47
	v_mov_b32_e32 v46, v48
	v_mov_b32_e32 v47, v106
	ds_write2_b64 v108, v[52:53], v[112:113] offset1:16
	ds_write2_b64 v108, v[110:111], v[46:47] offset0:128 offset1:144
	v_mov_b32_e32 v106, v49
	v_mfma_f32_16x16x32_bf16 v[46:49], v[78:81], v[18:21], 0
	v_mfma_f32_16x16x32_bf16 v[110:113], v[78:81], v[14:17], 0
	s_nop 6
	v_mov_b32_e32 v52, v46
	v_mov_b32_e32 v53, v110
	v_mov_b32_e32 v110, v47
	v_mov_b32_e32 v46, v48
	v_mov_b32_e32 v47, v112
	ds_write2_b64 v108, v[46:47], v[102:103] offset0:160 offset1:192
	v_mov_b32_e32 v112, v49
	v_mfma_f32_16x16x32_bf16 v[46:49], v[78:81], v[10:13], 0
	ds_write2_b64 v108, v[52:53], v[100:101] offset0:32 offset1:64
	ds_write2_b64 v108, v[104:105], v[110:111] offset0:80 offset1:96
	ds_write2_b64 v108, v[106:107], v[112:113] offset0:208 offset1:224
	v_mfma_f32_16x16x32_bf16 v[78:81], v[78:81], v[6:9], 0
	v_add_u32_e32 v100, 0x80, v98
	s_nop 2
	v_mov_b32_e32 v52, v46
	v_mov_b32_e32 v46, v48
	v_xor_b32_e32 v48, 0x80000000, v87
	v_add_u32_e32 v101, 0x90, v98
	v_mov_b32_e32 v53, v78
	v_mov_b32_e32 v78, v47
	v_mov_b32_e32 v47, v80
	v_mov_b32_e32 v80, v49
	ds_write2st64_b64 v99, v[52:53], v[78:79] offset0:8 offset1:9
	ds_write2st64_b64 v99, v[46:47], v[80:81] offset0:10 offset1:11
	s_waitcnt lgkmcnt(0)
	ds_read_b64 v[140:141], v90 offset:4096
	ds_read_b64 v[142:143], v90 offset:4608
	ds_read_b64 v[144:145], v90 offset:5120
	ds_read_b64 v[146:147], v90 offset:5632
	ds_read_b64 v[148:149], v90 offset:6144
	ds_read_b64 v[150:151], v90 offset:6656
	ds_read_b64 v[152:153], v90 offset:7168
	ds_read_b64 v[154:155], v90 offset:7680
	v_mov_b32_e32 v49, v86
	v_pk_mul_f32 v[48:49], v[0:1], v[48:49] op_sel_hi:[0,1]
	v_pk_fma_f32 v[48:49], v[84:85], v[86:87], v[48:49] op_sel_hi:[0,1,1]
	v_add_u32_e32 v78, 32, v98
	s_waitcnt lgkmcnt(7)
	v_pk_add_f32 v[46:47], v[48:49], v[140:141]
	ds_write2st64_b32 v98, v46, v47 offset1:1
	v_xor_b32_e32 v52, 0x80000000, v47
	v_mov_b32_e32 v53, v46
	v_pk_mul_f32 v[52:53], v[0:1], v[52:53] op_sel_hi:[0,1]
	v_pk_fma_f32 v[46:47], v[84:85], v[46:47], v[52:53] op_sel_hi:[0,1,1]
	s_waitcnt lgkmcnt(7)
	v_pk_add_f32 v[46:47], v[142:143], v[46:47]
	ds_write2_b32 v98, v46, v47 offset0:132 offset1:196
	v_xor_b32_e32 v52, 0x80000000, v47
	v_mov_b32_e32 v53, v46
	v_pk_mul_f32 v[52:53], v[0:1], v[52:53] op_sel_hi:[0,1]
	v_pk_fma_f32 v[46:47], v[84:85], v[46:47], v[52:53] op_sel_hi:[0,1,1]
	s_waitcnt lgkmcnt(7)
	v_pk_add_f32 v[46:47], v[144:145], v[46:47]
	ds_write2st64_b32 v78, v46, v47 offset0:4 offset1:5
	v_xor_b32_e32 v52, 0x80000000, v47
	v_mov_b32_e32 v53, v46
	v_pk_mul_f32 v[52:53], v[0:1], v[52:53] op_sel_hi:[0,1]
	v_pk_fma_f32 v[46:47], v[84:85], v[46:47], v[52:53] op_sel_hi:[0,1,1]
	s_waitcnt lgkmcnt(7)
	v_pk_add_f32 v[46:47], v[146:147], v[46:47]
	v_add_u32_e32 v79, 48, v98
	ds_write2st64_b32 v79, v46, v47 offset0:6 offset1:7
	v_xor_b32_e32 v52, 0x80000000, v47
	v_mov_b32_e32 v53, v46
	v_pk_mul_f32 v[52:53], v[0:1], v[52:53] op_sel_hi:[0,1]
	v_pk_fma_f32 v[46:47], v[84:85], v[46:47], v[52:53] op_sel_hi:[0,1,1]
	s_waitcnt lgkmcnt(7)
; __device__ __forceinline__ float bf2f(bf16_t v) { return __uint_as_float(((unsigned)v) << 16); }
; __device__ __forceinline__ void s5_pass2_item(PP p, unsigned char* shm, int item, int l) {
;     ...
;     for (int sc = 0; sc < 4; ++sc) {
;         s5_bu16(f, uf[sc], buL, lane);
;         __syncthreads();
; #pragma unroll
;         for (int t = 0; t < 16; ++t) { s5_rec(q, *(const f32x2*)(buL + (t * 64 + lane) * 2), x); xs[t * 132 + lane] = x.x; xs[t * 132 + 64 + lane] = x.y; }
;         __syncthreads();
;         f32x4 y0 = (f32x4){0.f, 0.f, 0.f, 0.f}, y1 = y0;
;         const f32x4* xrow = (const f32x4*)(xs + cc * 132 + quad * 32);
; #pragma unroll
;         for (int i = 0; i < 8; ++i) { const f32x4 xv = xrow[i];
;             y0 = __builtin_amdgcn_mfma_f32_16x16x4f32(xv[0], cmr[4 * i + 0], y0, 0, 0, 0);
;             y1 = __builtin_amdgcn_mfma_f32_16x16x4f32(xv[1], cmr[4 * i + 1], y1, 0, 0, 0);
;             y0 = __builtin_amdgcn_mfma_f32_16x16x4f32(xv[2], cmr[4 * i + 2], y0, 0, 0, 0);
;             y1 = __builtin_amdgcn_mfma_f32_16x16x4f32(xv[3], cmr[4 * i + 3], y1, 0, 0, 0); }
;         const f32x4 y = y0 + y1;
; #pragma unroll
;         for (int r = 0; r < 4; ++r) { const int tl = sc * 16 + quad * 4 + r;
;             const float v = y[r] + dsk * bf2f(proj[PJ_UA + (row0 + tl) * 512 + g * 16 + cc]);
	v_pk_add_f32 v[46:47], v[148:149], v[46:47]
	v_add_u32_e32 v80, 64, v98
	ds_write2st64_b32 v80, v46, v47 offset0:8 offset1:9
	v_xor_b32_e32 v52, 0x80000000, v47
	v_mov_b32_e32 v53, v46
	v_pk_mul_f32 v[52:53], v[0:1], v[52:53] op_sel_hi:[0,1]
	v_pk_fma_f32 v[46:47], v[84:85], v[46:47], v[52:53] op_sel_hi:[0,1,1]
	s_waitcnt lgkmcnt(7)
	v_pk_add_f32 v[46:47], v[150:151], v[46:47]
	v_add_u32_e32 v81, 0x50, v98
	ds_write2st64_b32 v81, v46, v47 offset0:10 offset1:11
	v_xor_b32_e32 v52, 0x80000000, v47
	v_mov_b32_e32 v53, v46
	v_pk_mul_f32 v[52:53], v[0:1], v[52:53] op_sel_hi:[0,1]
	v_pk_fma_f32 v[46:47], v[84:85], v[46:47], v[52:53] op_sel_hi:[0,1,1]
	s_waitcnt lgkmcnt(7)
	v_pk_add_f32 v[46:47], v[152:153], v[46:47]
	v_add_u32_e32 v86, 0x60, v98
	ds_write2st64_b32 v86, v46, v47 offset0:12 offset1:13
	v_xor_b32_e32 v52, 0x80000000, v47
	v_mov_b32_e32 v53, v46
	v_pk_mul_f32 v[52:53], v[0:1], v[52:53] op_sel_hi:[0,1]
	v_pk_fma_f32 v[46:47], v[84:85], v[46:47], v[52:53] op_sel_hi:[0,1,1]
	s_waitcnt lgkmcnt(7)
	v_pk_add_f32 v[46:47], v[154:155], v[46:47]
	v_add_u32_e32 v87, 0x70, v98
	ds_write2st64_b32 v87, v46, v47 offset0:14 offset1:15
	ds_read_b64 v[140:141], v90 offset:8192
	ds_read_b64 v[142:143], v90 offset:8704
	ds_read_b64 v[144:145], v90 offset:9216
	ds_read_b64 v[146:147], v90 offset:9728
	ds_read_b64 v[148:149], v90 offset:10240
	ds_read_b64 v[150:151], v90 offset:10752
	ds_read_b64 v[152:153], v90 offset:11264
	ds_read_b64 v[154:155], v90 offset:11776
	v_xor_b32_e32 v52, 0x80000000, v47
	v_mov_b32_e32 v53, v46
	v_pk_mul_f32 v[52:53], v[0:1], v[52:53] op_sel_hi:[0,1]
	v_pk_fma_f32 v[46:47], v[84:85], v[46:47], v[52:53] op_sel_hi:[0,1,1]
	s_waitcnt lgkmcnt(7)
	v_pk_add_f32 v[46:47], v[140:141], v[46:47]
	ds_write2st64_b32 v100, v46, v47 offset0:16 offset1:17
	v_xor_b32_e32 v52, 0x80000000, v47
	v_mov_b32_e32 v53, v46
	v_pk_mul_f32 v[52:53], v[0:1], v[52:53] op_sel_hi:[0,1]
	v_pk_fma_f32 v[46:47], v[84:85], v[46:47], v[52:53] op_sel_hi:[0,1,1]
	s_waitcnt lgkmcnt(7)
	v_pk_add_f32 v[46:47], v[142:143], v[46:47]
	ds_write2st64_b32 v101, v46, v47 offset0:18 offset1:19
	v_xor_b32_e32 v52, 0x80000000, v47
	v_mov_b32_e32 v53, v46
	v_pk_mul_f32 v[52:53], v[0:1], v[52:53] op_sel_hi:[0,1]
	v_pk_fma_f32 v[46:47], v[84:85], v[46:47], v[52:53] op_sel_hi:[0,1,1]
	s_waitcnt lgkmcnt(7)
	v_pk_add_f32 v[46:47], v[144:145], v[46:47]
	v_add_u32_e32 v102, 0xa0, v98
	ds_write2st64_b32 v102, v46, v47 offset0:20 offset1:21
	v_xor_b32_e32 v52, 0x80000000, v47
	v_mov_b32_e32 v53, v46
	v_pk_mul_f32 v[52:53], v[0:1], v[52:53] op_sel_hi:[0,1]
	v_pk_fma_f32 v[46:47], v[84:85], v[46:47], v[52:53] op_sel_hi:[0,1,1]
	s_waitcnt lgkmcnt(7)
	v_pk_add_f32 v[46:47], v[146:147], v[46:47]
	v_add_u32_e32 v103, 0xb0, v98
	ds_write2st64_b32 v103, v46, v47 offset0:22 offset1:23
	v_xor_b32_e32 v52, 0x80000000, v47
	v_mov_b32_e32 v53, v46
	v_pk_mul_f32 v[52:53], v[0:1], v[52:53] op_sel_hi:[0,1]
	v_pk_fma_f32 v[46:47], v[84:85], v[46:47], v[52:53] op_sel_hi:[0,1,1]
	s_waitcnt lgkmcnt(7)
	v_pk_add_f32 v[46:47], v[148:149], v[46:47]
	v_add_u32_e32 v104, 0xc0, v98
	ds_write2st64_b32 v104, v46, v47 offset0:24 offset1:25
	v_xor_b32_e32 v52, 0x80000000, v47
	v_mov_b32_e32 v53, v46
	v_pk_mul_f32 v[52:53], v[0:1], v[52:53] op_sel_hi:[0,1]
	v_pk_fma_f32 v[46:47], v[84:85], v[46:47], v[52:53] op_sel_hi:[0,1,1]
	s_waitcnt lgkmcnt(7)
	v_pk_add_f32 v[46:47], v[150:151], v[46:47]
	v_add_u32_e32 v105, 0xd0, v98
	ds_write2st64_b32 v105, v46, v47 offset0:26 offset1:27
	v_xor_b32_e32 v52, 0x80000000, v47
	v_mov_b32_e32 v53, v46
	v_pk_mul_f32 v[52:53], v[0:1], v[52:53] op_sel_hi:[0,1]
	v_pk_fma_f32 v[46:47], v[84:85], v[46:47], v[52:53] op_sel_hi:[0,1,1]
	s_waitcnt lgkmcnt(7)
	v_pk_add_f32 v[46:47], v[152:153], v[46:47]
	v_add_u32_e32 v106, 0xe0, v98
	ds_write2st64_b32 v106, v46, v47 offset0:28 offset1:29
	v_xor_b32_e32 v52, 0x80000000, v47
	v_mov_b32_e32 v53, v46
	v_pk_mul_f32 v[52:53], v[0:1], v[52:53] op_sel_hi:[0,1]
	v_pk_fma_f32 v[46:47], v[84:85], v[46:47], v[52:53] op_sel_hi:[0,1,1]
	s_waitcnt lgkmcnt(7)
	v_pk_add_f32 v[52:53], v[154:155], v[46:47]
	v_add_u32_e32 v107, 0xf0, v98
	ds_write2st64_b32 v107, v52, v53 offset0:30 offset1:31
	s_waitcnt lgkmcnt(0)
	v_mov_b32_e32 v216, v82
	v_mov_b32_e32 v217, v83
	v_lshlrev_b64 v[216:217], 9, v[216:217]
	v_lshl_add_u64 v[216:217], v[216:217], 0, v[50:51]
	v_lshlrev_b64 v[216:217], 1, v[216:217]
	v_lshl_add_u64 v[216:217], s[8:9], 0, v[216:217]
	global_load_ushort v200, v[216:217], off
	global_load_ushort v201, v[216:217], off offset:1024
	global_load_ushort v202, v[216:217], off offset:2048
	global_load_ushort v203, v[216:217], off offset:3072
	ds_read_b128 v[46:49], v89
	ds_read_b128 v[110:113], v89 offset:16
	ds_read_b128 v[114:117], v89 offset:32
	ds_read_b128 v[118:121], v89 offset:48
	s_waitcnt lgkmcnt(3)
	v_mfma_f32_16x16x4_f32 v[122:125], v46, v97, 0
	v_mfma_f32_16x16x4_f32 v[126:129], v47, v96, 0
	v_mfma_f32_16x16x4_f32 v[122:125], v48, v95, v[122:125]
	v_mfma_f32_16x16x4_f32 v[46:49], v49, v94, v[126:129]
	s_waitcnt lgkmcnt(2)
	v_mfma_f32_16x16x4_f32 v[122:125], v110, v93, v[122:125]
	v_mfma_f32_16x16x4_f32 v[46:49], v111, v92, v[46:49]
	v_mfma_f32_16x16x4_f32 v[122:125], v112, v91, v[122:125]
	v_mfma_f32_16x16x4_f32 v[46:49], v113, v88, v[46:49]
	s_waitcnt lgkmcnt(1)
	v_mfma_f32_16x16x4_f32 v[110:113], v114, v85, v[122:125]
	v_mfma_f32_16x16x4_f32 v[46:49], v115, v55, v[46:49]
	v_mfma_f32_16x16x4_f32 v[110:113], v116, v56, v[110:113]
	v_mfma_f32_16x16x4_f32 v[46:49], v117, v57, v[46:49]
	ds_read_b128 v[114:117], v89 offset:64
	s_waitcnt lgkmcnt(1)
; __device__ __forceinline__ float bf2f(bf16_t v) { return __uint_as_float(((unsigned)v) << 16); }
; __device__ __forceinline__ bf16_t f2bf(float f) { unsigned u = __float_as_uint(f); u += 0x7FFFu + ((u >> 16) & 1u); return (bf16_t)(u >> 16); }
; __device__ __forceinline__ void s5_pass2_item(PP p, unsigned char* shm, int item, int l) {
;     ...
;         f32x4 y0 = (f32x4){0.f, 0.f, 0.f, 0.f}, y1 = y0;
;         const f32x4* xrow = (const f32x4*)(xs + cc * 132 + quad * 32);
; #pragma unroll
;         for (int i = 0; i < 8; ++i) { const f32x4 xv = xrow[i];
;             y0 = __builtin_amdgcn_mfma_f32_16x16x4f32(xv[0], cmr[4 * i + 0], y0, 0, 0, 0);
;             y1 = __builtin_amdgcn_mfma_f32_16x16x4f32(xv[1], cmr[4 * i + 1], y1, 0, 0, 0);
;             y0 = __builtin_amdgcn_mfma_f32_16x16x4f32(xv[2], cmr[4 * i + 2], y0, 0, 0, 0);
;             y1 = __builtin_amdgcn_mfma_f32_16x16x4f32(xv[3], cmr[4 * i + 3], y1, 0, 0, 0); }
;         const f32x4 y = y0 + y1;
; #pragma unroll
;         for (int r = 0; r < 4; ++r) { const int tl = sc * 16 + quad * 4 + r;
;             const float v = y[r] + dsk * bf2f(proj[PJ_UA + (row0 + tl) * 512 + g * 16 + cc]);
;             const float z = 0.7978845608028654f * (v + 0.044715f * v * v * v);
;             const float th = 1.0f - 2.0f / (__expf(2.0f * z) + 1.0f);
;             Gout[(row0 + tl) * 512 + g * 16 + cc] = f2bf(0.5f * v * (1.0f + th)); }
	v_mfma_f32_16x16x4_f32 v[110:113], v118, v58, v[110:113]
	v_mfma_f32_16x16x4_f32 v[46:49], v119, v59, v[46:49]
	v_mfma_f32_16x16x4_f32 v[110:113], v120, v60, v[110:113]
	v_mfma_f32_16x16x4_f32 v[46:49], v121, v61, v[46:49]
	s_waitcnt lgkmcnt(0)
	v_mfma_f32_16x16x4_f32 v[110:113], v114, v62, v[110:113]
	v_mfma_f32_16x16x4_f32 v[46:49], v115, v63, v[46:49]
	v_mfma_f32_16x16x4_f32 v[110:113], v116, v64, v[110:113]
	v_mfma_f32_16x16x4_f32 v[46:49], v117, v65, v[46:49]
	ds_read_b128 v[114:117], v89 offset:80
	s_waitcnt lgkmcnt(0)
	v_mfma_f32_16x16x4_f32 v[110:113], v114, v66, v[110:113]
	v_mfma_f32_16x16x4_f32 v[46:49], v115, v67, v[46:49]
	v_mfma_f32_16x16x4_f32 v[110:113], v116, v68, v[110:113]
	v_mfma_f32_16x16x4_f32 v[46:49], v117, v69, v[46:49]
	ds_read_b128 v[114:117], v89 offset:96
	s_waitcnt lgkmcnt(0)
	v_mfma_f32_16x16x4_f32 v[110:113], v114, v70, v[110:113]
	v_mfma_f32_16x16x4_f32 v[46:49], v115, v71, v[46:49]
	v_mfma_f32_16x16x4_f32 v[110:113], v116, v72, v[110:113]
	v_mfma_f32_16x16x4_f32 v[46:49], v117, v73, v[46:49]
	ds_read_b128 v[114:117], v89 offset:112
	s_waitcnt lgkmcnt(0)
	v_mfma_f32_16x16x4_f32 v[110:113], v114, v74, v[110:113]
	v_mfma_f32_16x16x4_f32 v[46:49], v115, v75, v[46:49]
	v_mfma_f32_16x16x4_f32 v[110:113], v116, v76, v[110:113]
	v_mfma_f32_16x16x4_f32 v[46:49], v117, v77, v[46:49]
	s_nop 9
	v_pk_add_f32 v[46:47], v[110:111], v[46:47]
	v_lshlrev_b64 v[110:111], 9, v[82:83]
	v_lshl_add_u64 v[110:111], v[110:111], 0, v[50:51]
	v_lshlrev_b64 v[110:111], 1, v[110:111]
	v_pk_add_f32 v[48:49], v[112:113], v[48:49]
	v_lshl_add_u64 v[112:113], s[8:9], 0, v[110:111]
	v_lshl_add_u64 v[110:111], s[28:29], 0, v[110:111]
	s_waitcnt vmcnt(3)
	v_lshlrev_b32_e32 v109, 16, v200
	v_fma_f32 v46, v54, v109, v46
	v_mul_f32_e32 v109, 0x3d372713, v46
	v_mul_f32_e32 v109, v46, v109
	v_fma_f32 v109, v46, v109, v46
	v_mul_f32_e32 v109, 0x3f4c422a, v109
	v_add_f32_e32 v109, v109, v109
	v_mul_f32_e32 v109, 0x3fb8aa3b, v109
	v_exp_f32_e32 v109, v109
	v_mul_f32_e32 v46, 0.5, v46
	v_add_f32_e32 v109, 1.0, v109
	v_div_scale_f32 v112, s[2:3], v109, v109, 2.0
	v_rcp_f32_e32 v113, v112
	s_nop 0
	v_fma_f32 v114, -v112, v113, 1.0
	v_fmac_f32_e32 v113, v114, v113
	v_div_scale_f32 v114, vcc, 2.0, v109, 2.0
	v_mul_f32_e32 v115, v114, v113
	v_fma_f32 v116, -v112, v115, v114
	v_fmac_f32_e32 v115, v116, v113
	v_fma_f32 v112, -v112, v115, v114
	v_div_fmas_f32 v112, v112, v113, v115
	v_div_fixup_f32 v109, v112, v109, 2.0
	v_sub_f32_e32 v109, 1.0, v109
	v_add_f32_e32 v109, 1.0, v109
	v_mul_f32_e32 v46, v46, v109
	v_bfe_u32 v109, v46, 16, 1
	v_add3_u32 v46, v46, v109, s31
	global_store_short_d16_hi v[110:111], v46, off
	v_or_b32_e32 v110, 1, v82
	v_mov_b32_e32 v111, v83
	v_lshlrev_b64 v[110:111], 9, v[110:111]
	v_lshl_add_u64 v[110:111], v[110:111], 0, v[50:51]
	v_lshlrev_b64 v[110:111], 1, v[110:111]
	v_lshl_add_u64 v[112:113], s[8:9], 0, v[110:111]
	s_waitcnt vmcnt(3)
	v_lshlrev_b32_e32 v46, 16, v201
	v_fmac_f32_e32 v47, v54, v46
	v_mul_f32_e32 v46, 0x3d372713, v47
	v_mul_f32_e32 v46, v47, v46
	v_fma_f32 v46, v47, v46, v47
	v_mul_f32_e32 v46, 0x3f4c422a, v46
	v_add_f32_e32 v46, v46, v46
	v_mul_f32_e32 v46, 0x3fb8aa3b, v46
	v_exp_f32_e32 v46, v46
	v_mul_f32_e32 v47, 0.5, v47
	v_add_f32_e32 v46, 1.0, v46
	v_div_scale_f32 v109, s[2:3], v46, v46, 2.0
	v_rcp_f32_e32 v112, v109
	s_nop 0
	v_fma_f32 v113, -v109, v112, 1.0
	v_fmac_f32_e32 v112, v113, v112
	v_div_scale_f32 v113, vcc, 2.0, v46, 2.0
	v_mul_f32_e32 v114, v113, v112
	v_fma_f32 v115, -v109, v114, v113
	v_fmac_f32_e32 v114, v115, v112
	v_fma_f32 v109, -v109, v114, v113
	v_div_fmas_f32 v109, v109, v112, v114
	v_div_fixup_f32 v46, v109, v46, 2.0
	v_sub_f32_e32 v46, 1.0, v46
	v_add_f32_e32 v46, 1.0, v46
	v_mul_f32_e32 v46, v47, v46
	v_bfe_u32 v47, v46, 16, 1
	v_add3_u32 v109, v46, v47, s31
	v_lshl_add_u64 v[46:47], s[28:29], 0, v[110:111]
	global_store_short_d16_hi v[46:47], v109, off
	v_or_b32_e32 v46, 2, v82
	v_mov_b32_e32 v47, v83
	v_lshlrev_b64 v[46:47], 9, v[46:47]
	v_lshl_add_u64 v[46:47], v[46:47], 0, v[50:51]
	v_lshlrev_b64 v[46:47], 1, v[46:47]
	v_lshl_add_u64 v[110:111], s[8:9], 0, v[46:47]
	v_lshl_add_u64 v[46:47], s[28:29], 0, v[46:47]
	s_waitcnt vmcnt(3)
	v_lshlrev_b32_e32 v109, 16, v202
	v_fma_f32 v48, v54, v109, v48
	v_mul_f32_e32 v109, 0x3d372713, v48
	v_mul_f32_e32 v109, v48, v109
	v_fma_f32 v109, v48, v109, v48
	v_mul_f32_e32 v109, 0x3f4c422a, v109
	v_add_f32_e32 v109, v109, v109
	v_mul_f32_e32 v109, 0x3fb8aa3b, v109
	v_exp_f32_e32 v109, v109
	v_mul_f32_e32 v48, 0.5, v48
	v_add_f32_e32 v109, 1.0, v109
	v_div_scale_f32 v110, s[2:3], v109, v109, 2.0
	v_rcp_f32_e32 v111, v110
	s_nop 0
	v_fma_f32 v112, -v110, v111, 1.0
	v_fmac_f32_e32 v111, v112, v111
	v_div_scale_f32 v112, vcc, 2.0, v109, 2.0
	v_mul_f32_e32 v113, v112, v111
	v_fma_f32 v114, -v110, v113, v112
	v_fmac_f32_e32 v113, v114, v111
	v_fma_f32 v110, -v110, v113, v112
	v_div_fmas_f32 v110, v110, v111, v113
	v_div_fixup_f32 v109, v110, v109, 2.0
	v_sub_f32_e32 v109, 1.0, v109
	v_add_f32_e32 v109, 1.0, v109
	v_mul_f32_e32 v48, v48, v109
	v_bfe_u32 v109, v48, 16, 1
	v_add3_u32 v48, v48, v109, s31
	global_store_short_d16_hi v[46:47], v48, off
	v_or_b32_e32 v46, 3, v82
	v_mov_b32_e32 v47, v83
	v_lshlrev_b64 v[46:47], 9, v[46:47]
	v_lshl_add_u64 v[46:47], v[46:47], 0, v[50:51]
	v_lshlrev_b64 v[46:47], 1, v[46:47]
	v_lshl_add_u64 v[110:111], s[8:9], 0, v[46:47]
	v_lshl_add_u64 v[46:47], s[28:29], 0, v[46:47]
	v_mfma_f32_16x16x32_bf16 v[114:117], v[42:45], v[30:33], 0
	s_waitcnt vmcnt(3)
; __device__ __forceinline__ float bf2f(bf16_t v) { return __uint_as_float(((unsigned)v) << 16); }
; __device__ __forceinline__ bf16_t f2bf(float f) { unsigned u = __float_as_uint(f); u += 0x7FFFu + ((u >> 16) & 1u); return (bf16_t)(u >> 16); }
; __device__ __forceinline__ void s5_pass2_item(PP p, unsigned char* shm, int item, int l) {
;     ...
;     for (int sc = 0; sc < 4; ++sc) {
;         s5_bu16(f, uf[sc], buL, lane);
;         __syncthreads();
; #pragma unroll
;         for (int t = 0; t < 16; ++t) { s5_rec(q, *(const f32x2*)(buL + (t * 64 + lane) * 2), x); xs[t * 132 + lane] = x.x; xs[t * 132 + 64 + lane] = x.y; }
;         __syncthreads();
;         f32x4 y0 = (f32x4){0.f, 0.f, 0.f, 0.f}, y1 = y0;
;         const f32x4* xrow = (const f32x4*)(xs + cc * 132 + quad * 32);
; #pragma unroll
;         for (int i = 0; i < 8; ++i) { const f32x4 xv = xrow[i];
;             y0 = __builtin_amdgcn_mfma_f32_16x16x4f32(xv[0], cmr[4 * i + 0], y0, 0, 0, 0);
;             y1 = __builtin_amdgcn_mfma_f32_16x16x4f32(xv[1], cmr[4 * i + 1], y1, 0, 0, 0);
;             y0 = __builtin_amdgcn_mfma_f32_16x16x4f32(xv[2], cmr[4 * i + 2], y0, 0, 0, 0);
;             y1 = __builtin_amdgcn_mfma_f32_16x16x4f32(xv[3], cmr[4 * i + 3], y1, 0, 0, 0); }
;         const f32x4 y = y0 + y1;
; #pragma unroll
;         for (int r = 0; r < 4; ++r) { const int tl = sc * 16 + quad * 4 + r;
;             const float v = y[r] + dsk * bf2f(proj[PJ_UA + (row0 + tl) * 512 + g * 16 + cc]);
;             const float z = 0.7978845608028654f * (v + 0.044715f * v * v * v);
;             const float th = 1.0f - 2.0f / (__expf(2.0f * z) + 1.0f);
;             Gout[(row0 + tl) * 512 + g * 16 + cc] = f2bf(0.5f * v * (1.0f + th)); }
;         __syncthreads();
	v_lshlrev_b32_e32 v48, 16, v203
	v_fmac_f32_e32 v49, v54, v48
	v_mul_f32_e32 v48, 0x3d372713, v49
	v_mul_f32_e32 v48, v49, v48
	v_fma_f32 v48, v49, v48, v49
	v_mul_f32_e32 v48, 0x3f4c422a, v48
	v_add_f32_e32 v48, v48, v48
	v_mul_f32_e32 v48, 0x3fb8aa3b, v48
	v_exp_f32_e32 v48, v48
	v_mul_f32_e32 v49, 0.5, v49
	v_mov_b32_e32 v123, v114
	v_add_f32_e32 v48, 1.0, v48
	v_div_scale_f32 v109, s[2:3], v48, v48, 2.0
	v_rcp_f32_e32 v110, v109
	s_nop 0
	v_fma_f32 v111, -v109, v110, 1.0
	v_fmac_f32_e32 v110, v111, v110
	v_div_scale_f32 v111, vcc, 2.0, v48, 2.0
	v_mul_f32_e32 v112, v111, v110
	v_fma_f32 v113, -v109, v112, v111
	v_fmac_f32_e32 v112, v113, v110
	v_fma_f32 v109, -v109, v112, v111
	v_div_fmas_f32 v109, v109, v110, v112
	v_div_fixup_f32 v48, v109, v48, 2.0
	v_sub_f32_e32 v48, 1.0, v48
	v_add_f32_e32 v48, 1.0, v48
	v_mul_f32_e32 v48, v49, v48
	v_bfe_u32 v49, v48, 16, 1
	v_add3_u32 v48, v48, v49, s31
	global_store_short_d16_hi v[46:47], v48, off
	v_mfma_f32_16x16x32_bf16 v[46:49], v[42:45], v[26:29], 0
	v_mfma_f32_16x16x32_bf16 v[110:113], v[42:45], v[34:37], 0
	s_nop 5
	v_mov_b32_e32 v118, v46
	s_nop 0
	v_mov_b32_e32 v119, v110
	v_mov_b32_e32 v110, v47
	v_mov_b32_e32 v120, v48
	v_mov_b32_e32 v121, v112
	v_mov_b32_e32 v112, v49
	v_mfma_f32_16x16x32_bf16 v[46:49], v[42:45], v[22:25], 0
	s_nop 7
	v_mov_b32_e32 v122, v46
	v_mov_b32_e32 v114, v47
	v_mov_b32_e32 v46, v48
	v_mov_b32_e32 v47, v116
	ds_write2_b64 v108, v[118:119], v[122:123] offset1:16
	ds_write2_b64 v108, v[120:121], v[46:47] offset0:128 offset1:144
	v_mov_b32_e32 v116, v49
	v_mfma_f32_16x16x32_bf16 v[46:49], v[42:45], v[18:21], 0
	v_mfma_f32_16x16x32_bf16 v[118:121], v[42:45], v[14:17], 0
	s_nop 6
	v_mov_b32_e32 v122, v46
	v_mov_b32_e32 v123, v118
	v_mov_b32_e32 v118, v47
	v_mov_b32_e32 v46, v48
	v_mov_b32_e32 v47, v120
	ds_write2_b64 v108, v[46:47], v[112:113] offset0:160 offset1:192
	v_mov_b32_e32 v120, v49
	v_mfma_f32_16x16x32_bf16 v[46:49], v[42:45], v[10:13], 0
	ds_write2_b64 v108, v[122:123], v[110:111] offset0:32 offset1:64
	ds_write2_b64 v108, v[114:115], v[118:119] offset0:80 offset1:96
	ds_write2_b64 v108, v[116:117], v[120:121] offset0:208 offset1:224
	v_mfma_f32_16x16x32_bf16 v[42:45], v[42:45], v[6:9], 0
	s_nop 3
	v_mov_b32_e32 v110, v46
	s_nop 2
	v_mov_b32_e32 v111, v42
	v_mov_b32_e32 v42, v47
	ds_write2st64_b64 v99, v[110:111], v[42:43] offset0:8 offset1:9
	v_mov_b32_e32 v42, v48
	v_mov_b32_e32 v43, v44
	v_mov_b32_e32 v44, v49
	ds_write2st64_b64 v99, v[42:43], v[44:45] offset0:10 offset1:11
	s_waitcnt lgkmcnt(0)
	ds_read_b64 v[140:141], v90 offset:4096
	ds_read_b64 v[142:143], v90 offset:4608
	ds_read_b64 v[144:145], v90 offset:5120
	ds_read_b64 v[146:147], v90 offset:5632
	ds_read_b64 v[148:149], v90 offset:6144
	ds_read_b64 v[150:151], v90 offset:6656
	ds_read_b64 v[152:153], v90 offset:7168
	ds_read_b64 v[154:155], v90 offset:7680
	v_xor_b32_e32 v44, 0x80000000, v53
	v_mov_b32_e32 v45, v52
	v_pk_mul_f32 v[44:45], v[0:1], v[44:45] op_sel_hi:[0,1]
	v_pk_fma_f32 v[44:45], v[84:85], v[52:53], v[44:45] op_sel_hi:[0,1,1]
	s_waitcnt lgkmcnt(7)
	v_pk_add_f32 v[42:43], v[44:45], v[140:141]
	ds_write2st64_b32 v98, v42, v43 offset1:1
	v_xor_b32_e32 v46, 0x80000000, v43
	v_mov_b32_e32 v47, v42
	v_pk_mul_f32 v[46:47], v[0:1], v[46:47] op_sel_hi:[0,1]
	v_pk_fma_f32 v[42:43], v[84:85], v[42:43], v[46:47] op_sel_hi:[0,1,1]
	s_waitcnt lgkmcnt(7)
	v_pk_add_f32 v[42:43], v[142:143], v[42:43]
	ds_write2_b32 v98, v42, v43 offset0:132 offset1:196
	v_xor_b32_e32 v46, 0x80000000, v43
	v_mov_b32_e32 v47, v42
	v_pk_mul_f32 v[46:47], v[0:1], v[46:47] op_sel_hi:[0,1]
	v_pk_fma_f32 v[42:43], v[84:85], v[42:43], v[46:47] op_sel_hi:[0,1,1]
	s_waitcnt lgkmcnt(7)
	v_pk_add_f32 v[42:43], v[144:145], v[42:43]
	ds_write2st64_b32 v78, v42, v43 offset0:4 offset1:5
	v_xor_b32_e32 v46, 0x80000000, v43
	v_mov_b32_e32 v47, v42
	v_pk_mul_f32 v[46:47], v[0:1], v[46:47] op_sel_hi:[0,1]
	v_pk_fma_f32 v[42:43], v[84:85], v[42:43], v[46:47] op_sel_hi:[0,1,1]
	s_waitcnt lgkmcnt(7)
	v_pk_add_f32 v[42:43], v[146:147], v[42:43]
	ds_write2st64_b32 v79, v42, v43 offset0:6 offset1:7
	v_xor_b32_e32 v46, 0x80000000, v43
	v_mov_b32_e32 v47, v42
	v_pk_mul_f32 v[46:47], v[0:1], v[46:47] op_sel_hi:[0,1]
	v_pk_fma_f32 v[42:43], v[84:85], v[42:43], v[46:47] op_sel_hi:[0,1,1]
	s_waitcnt lgkmcnt(7)
	v_pk_add_f32 v[42:43], v[148:149], v[42:43]
	ds_write2st64_b32 v80, v42, v43 offset0:8 offset1:9
	v_xor_b32_e32 v46, 0x80000000, v43
	v_mov_b32_e32 v47, v42
	v_pk_mul_f32 v[46:47], v[0:1], v[46:47] op_sel_hi:[0,1]
	v_pk_fma_f32 v[42:43], v[84:85], v[42:43], v[46:47] op_sel_hi:[0,1,1]
	s_waitcnt lgkmcnt(7)
	v_pk_add_f32 v[42:43], v[150:151], v[42:43]
	ds_write2st64_b32 v81, v42, v43 offset0:10 offset1:11
	v_xor_b32_e32 v46, 0x80000000, v43
	v_mov_b32_e32 v47, v42
	v_pk_mul_f32 v[46:47], v[0:1], v[46:47] op_sel_hi:[0,1]
	v_pk_fma_f32 v[42:43], v[84:85], v[42:43], v[46:47] op_sel_hi:[0,1,1]
	s_waitcnt lgkmcnt(7)
	v_pk_add_f32 v[42:43], v[152:153], v[42:43]
	ds_write2st64_b32 v86, v42, v43 offset0:12 offset1:13
	v_xor_b32_e32 v46, 0x80000000, v43
	v_mov_b32_e32 v47, v42
	v_pk_mul_f32 v[46:47], v[0:1], v[46:47] op_sel_hi:[0,1]
	v_pk_fma_f32 v[42:43], v[84:85], v[42:43], v[46:47] op_sel_hi:[0,1,1]
	s_waitcnt lgkmcnt(7)
	v_pk_add_f32 v[42:43], v[154:155], v[42:43]
	ds_write2st64_b32 v87, v42, v43 offset0:14 offset1:15
	ds_read_b64 v[140:141], v90 offset:8192
	ds_read_b64 v[142:143], v90 offset:8704
	ds_read_b64 v[144:145], v90 offset:9216
	ds_read_b64 v[146:147], v90 offset:9728
	ds_read_b64 v[148:149], v90 offset:10240
	ds_read_b64 v[150:151], v90 offset:10752
	ds_read_b64 v[152:153], v90 offset:11264
	ds_read_b64 v[154:155], v90 offset:11776
	v_xor_b32_e32 v46, 0x80000000, v43
	v_mov_b32_e32 v47, v42
	v_pk_mul_f32 v[46:47], v[0:1], v[46:47] op_sel_hi:[0,1]
	v_pk_fma_f32 v[42:43], v[84:85], v[42:43], v[46:47] op_sel_hi:[0,1,1]
	s_waitcnt lgkmcnt(7)
; __device__ __forceinline__ void s5_pass2_item(PP p, unsigned char* shm, int item, int l) {
;     ...
;         __syncthreads();
; #pragma unroll
;         for (int t = 0; t < 16; ++t) { s5_rec(q, *(const f32x2*)(buL + (t * 64 + lane) * 2), x); xs[t * 132 + lane] = x.x; xs[t * 132 + 64 + lane] = x.y; }
;         __syncthreads();
;         f32x4 y0 = (f32x4){0.f, 0.f, 0.f, 0.f}, y1 = y0;
;         const f32x4* xrow = (const f32x4*)(xs + cc * 132 + quad * 32);
; #pragma unroll
;         for (int i = 0; i < 8; ++i) { const f32x4 xv = xrow[i];
;             y0 = __builtin_amdgcn_mfma_f32_16x16x4f32(xv[0], cmr[4 * i + 0], y0, 0, 0, 0);
;             y1 = __builtin_amdgcn_mfma_f32_16x16x4f32(xv[1], cmr[4 * i + 1], y1, 0, 0, 0);
;             y0 = __builtin_amdgcn_mfma_f32_16x16x4f32(xv[2], cmr[4 * i + 2], y0, 0, 0, 0);
;             y1 = __builtin_amdgcn_mfma_f32_16x16x4f32(xv[3], cmr[4 * i + 3], y1, 0, 0, 0); }
	v_pk_add_f32 v[42:43], v[140:141], v[42:43]
	ds_write2st64_b32 v100, v42, v43 offset0:16 offset1:17
	v_xor_b32_e32 v46, 0x80000000, v43
	v_mov_b32_e32 v47, v42
	v_pk_mul_f32 v[46:47], v[0:1], v[46:47] op_sel_hi:[0,1]
	v_pk_fma_f32 v[42:43], v[84:85], v[42:43], v[46:47] op_sel_hi:[0,1,1]
	s_waitcnt lgkmcnt(7)
	v_pk_add_f32 v[42:43], v[142:143], v[42:43]
	ds_write2st64_b32 v101, v42, v43 offset0:18 offset1:19
	v_xor_b32_e32 v46, 0x80000000, v43
	v_mov_b32_e32 v47, v42
	v_pk_mul_f32 v[46:47], v[0:1], v[46:47] op_sel_hi:[0,1]
	v_pk_fma_f32 v[42:43], v[84:85], v[42:43], v[46:47] op_sel_hi:[0,1,1]
	s_waitcnt lgkmcnt(7)
	v_pk_add_f32 v[42:43], v[144:145], v[42:43]
	ds_write2st64_b32 v102, v42, v43 offset0:20 offset1:21
	v_xor_b32_e32 v46, 0x80000000, v43
	v_mov_b32_e32 v47, v42
	v_pk_mul_f32 v[46:47], v[0:1], v[46:47] op_sel_hi:[0,1]
	v_pk_fma_f32 v[42:43], v[84:85], v[42:43], v[46:47] op_sel_hi:[0,1,1]
	s_waitcnt lgkmcnt(7)
	v_pk_add_f32 v[42:43], v[146:147], v[42:43]
	ds_write2st64_b32 v103, v42, v43 offset0:22 offset1:23
	v_xor_b32_e32 v46, 0x80000000, v43
	v_mov_b32_e32 v47, v42
	v_pk_mul_f32 v[46:47], v[0:1], v[46:47] op_sel_hi:[0,1]
	v_pk_fma_f32 v[42:43], v[84:85], v[42:43], v[46:47] op_sel_hi:[0,1,1]
	s_waitcnt lgkmcnt(7)
	v_pk_add_f32 v[42:43], v[148:149], v[42:43]
	ds_write2st64_b32 v104, v42, v43 offset0:24 offset1:25
	v_xor_b32_e32 v46, 0x80000000, v43
	v_mov_b32_e32 v47, v42
	v_pk_mul_f32 v[46:47], v[0:1], v[46:47] op_sel_hi:[0,1]
	v_pk_fma_f32 v[42:43], v[84:85], v[42:43], v[46:47] op_sel_hi:[0,1,1]
	s_waitcnt lgkmcnt(7)
	v_pk_add_f32 v[42:43], v[150:151], v[42:43]
	ds_write2st64_b32 v105, v42, v43 offset0:26 offset1:27
	v_xor_b32_e32 v46, 0x80000000, v43
	v_mov_b32_e32 v47, v42
	v_pk_mul_f32 v[46:47], v[0:1], v[46:47] op_sel_hi:[0,1]
	v_pk_fma_f32 v[42:43], v[84:85], v[42:43], v[46:47] op_sel_hi:[0,1,1]
	s_waitcnt lgkmcnt(7)
	v_pk_add_f32 v[42:43], v[152:153], v[42:43]
	ds_write2st64_b32 v106, v42, v43 offset0:28 offset1:29
	v_xor_b32_e32 v46, 0x80000000, v43
	v_mov_b32_e32 v47, v42
	v_pk_mul_f32 v[46:47], v[0:1], v[46:47] op_sel_hi:[0,1]
	v_pk_fma_f32 v[42:43], v[84:85], v[42:43], v[46:47] op_sel_hi:[0,1,1]
	s_waitcnt lgkmcnt(7)
	v_pk_add_f32 v[46:47], v[154:155], v[42:43]
	ds_write2st64_b32 v107, v46, v47 offset0:30 offset1:31
	s_waitcnt lgkmcnt(0)
	v_or_b32_e32 v216, 16, v82
	v_mov_b32_e32 v217, v83
	v_lshlrev_b64 v[216:217], 9, v[216:217]
	v_lshl_add_u64 v[216:217], v[216:217], 0, v[50:51]
	v_lshlrev_b64 v[216:217], 1, v[216:217]
	v_lshl_add_u64 v[216:217], s[8:9], 0, v[216:217]
	global_load_ushort v204, v[216:217], off
	global_load_ushort v205, v[216:217], off offset:1024
	global_load_ushort v206, v[216:217], off offset:2048
	global_load_ushort v207, v[216:217], off offset:3072
	ds_read_b128 v[42:45], v89
	ds_read_b128 v[110:113], v89 offset:16
	ds_read_b128 v[114:117], v89 offset:32
	ds_read_b128 v[118:121], v89 offset:48
	s_waitcnt lgkmcnt(3)
	v_mfma_f32_16x16x4_f32 v[122:125], v42, v97, 0
	v_or_b32_e32 v48, 16, v82
	v_mov_b32_e32 v49, v83
	v_lshlrev_b64 v[48:49], 9, v[48:49]
	v_lshl_add_u64 v[48:49], v[48:49], 0, v[50:51]
	v_lshlrev_b64 v[48:49], 1, v[48:49]
	v_lshl_add_u64 v[52:53], s[8:9], 0, v[48:49]
	v_mfma_f32_16x16x4_f32 v[126:129], v43, v96, 0
	v_lshl_add_u64 v[48:49], s[28:29], 0, v[48:49]
	s_waitcnt vmcnt(3)
	v_lshlrev_b32_e32 v52, 16, v204
	v_mfma_f32_16x16x4_f32 v[122:125], v44, v95, v[122:125]
	v_mfma_f32_16x16x4_f32 v[42:45], v45, v94, v[126:129]
	s_waitcnt lgkmcnt(2)
	v_mfma_f32_16x16x4_f32 v[122:125], v110, v93, v[122:125]
	v_mfma_f32_16x16x4_f32 v[42:45], v111, v92, v[42:45]
	v_mfma_f32_16x16x4_f32 v[122:125], v112, v91, v[122:125]
	v_mfma_f32_16x16x4_f32 v[42:45], v113, v88, v[42:45]
	s_waitcnt lgkmcnt(1)
	v_mfma_f32_16x16x4_f32 v[110:113], v114, v85, v[122:125]
	v_mfma_f32_16x16x4_f32 v[42:45], v115, v55, v[42:45]
	v_mfma_f32_16x16x4_f32 v[110:113], v116, v56, v[110:113]
	v_mfma_f32_16x16x4_f32 v[42:45], v117, v57, v[42:45]
	ds_read_b128 v[114:117], v89 offset:64
	s_waitcnt lgkmcnt(1)
	v_mfma_f32_16x16x4_f32 v[110:113], v118, v58, v[110:113]
	v_mfma_f32_16x16x4_f32 v[42:45], v119, v59, v[42:45]
	v_mfma_f32_16x16x4_f32 v[110:113], v120, v60, v[110:113]
	v_mfma_f32_16x16x4_f32 v[42:45], v121, v61, v[42:45]
	s_waitcnt lgkmcnt(0)
	v_mfma_f32_16x16x4_f32 v[110:113], v114, v62, v[110:113]
	v_mfma_f32_16x16x4_f32 v[42:45], v115, v63, v[42:45]
	v_mfma_f32_16x16x4_f32 v[110:113], v116, v64, v[110:113]
	v_mfma_f32_16x16x4_f32 v[42:45], v117, v65, v[42:45]
	ds_read_b128 v[114:117], v89 offset:80
	s_waitcnt lgkmcnt(0)
	v_mfma_f32_16x16x4_f32 v[110:113], v114, v66, v[110:113]
	v_mfma_f32_16x16x4_f32 v[42:45], v115, v67, v[42:45]
	v_mfma_f32_16x16x4_f32 v[110:113], v116, v68, v[110:113]
	v_mfma_f32_16x16x4_f32 v[42:45], v117, v69, v[42:45]
	ds_read_b128 v[114:117], v89 offset:96
	s_waitcnt lgkmcnt(0)
	v_mfma_f32_16x16x4_f32 v[110:113], v114, v70, v[110:113]
	v_mfma_f32_16x16x4_f32 v[42:45], v115, v71, v[42:45]
	v_mfma_f32_16x16x4_f32 v[110:113], v116, v72, v[110:113]
	v_mfma_f32_16x16x4_f32 v[42:45], v117, v73, v[42:45]
	ds_read_b128 v[114:117], v89 offset:112
	s_waitcnt lgkmcnt(0)
; __device__ __forceinline__ float bf2f(bf16_t v) { return __uint_as_float(((unsigned)v) << 16); }
; __device__ __forceinline__ bf16_t f2bf(float f) { unsigned u = __float_as_uint(f); u += 0x7FFFu + ((u >> 16) & 1u); return (bf16_t)(u >> 16); }
; __device__ __forceinline__ void s5_bu16(const S5Frag& f, const bf16x8 uf, float* buL, int lane) {
;     const int jj = lane & 15, quad = lane >> 4;
; #pragma unroll
;     for (int nt = 0; nt < 4; ++nt) {
;         const f32x4 z = (f32x4){0.f, 0.f, 0.f, 0.f};
;         const f32x4 dre = __builtin_amdgcn_mfma_f32_16x16x32_bf16(uf, f.bfr[nt], z, 0, 0, 0);
;         const f32x4 dim = __builtin_amdgcn_mfma_f32_16x16x32_bf16(uf, f.bfr[nt + 4], z, 0, 0, 0);
; #pragma unroll
;         for (int r = 0; r < 4; ++r) *(f32x2*)(buL + ((4 * quad + r) * 64 + 16 * nt + jj) * 2) = (f32x2){dre[r], dim[r]};
;     }
; }
; __device__ __forceinline__ void s5_pass2_item(PP p, unsigned char* shm, int item, int l) {
;     ...
;         const f32x4 y = y0 + y1;
; #pragma unroll
;         for (int r = 0; r < 4; ++r) { const int tl = sc * 16 + quad * 4 + r;
;             const float v = y[r] + dsk * bf2f(proj[PJ_UA + (row0 + tl) * 512 + g * 16 + cc]);
;             const float z = 0.7978845608028654f * (v + 0.044715f * v * v * v);
;             const float th = 1.0f - 2.0f / (__expf(2.0f * z) + 1.0f);
;             Gout[(row0 + tl) * 512 + g * 16 + cc] = f2bf(0.5f * v * (1.0f + th)); }
;         __syncthreads();
	v_mfma_f32_16x16x4_f32 v[110:113], v114, v74, v[110:113]
	v_mfma_f32_16x16x4_f32 v[42:45], v115, v75, v[42:45]
	v_mfma_f32_16x16x4_f32 v[110:113], v116, v76, v[110:113]
	v_mfma_f32_16x16x4_f32 v[42:45], v117, v77, v[42:45]
	v_mfma_f32_16x16x32_bf16 v[114:117], v[38:41], v[30:33], 0
	s_nop 8
	v_add_f32_e64 v42, v110, v42
	v_add_f32_e64 v43, v111, v43
	v_pk_add_f32 v[44:45], v[112:113], v[44:45]
	v_fma_f32 v42, v54, v52, v42
	v_mul_f32_e32 v52, 0x3d372713, v42
	v_mul_f32_e32 v52, v42, v52
	v_fma_f32 v52, v42, v52, v42
	v_mul_f32_e32 v52, 0x3f4c422a, v52
	v_add_f32_e32 v52, v52, v52
	v_mul_f32_e32 v52, 0x3fb8aa3b, v52
	v_exp_f32_e32 v52, v52
	v_mul_f32_e32 v42, 0.5, v42
	v_mov_b32_e32 v119, v114
	v_mfma_f32_16x16x32_bf16 v[30:33], v[2:5], v[30:33], 0
	v_add_f32_e32 v52, 1.0, v52
	v_div_scale_f32 v53, s[2:3], v52, v52, 2.0
	v_rcp_f32_e32 v109, v53
	s_nop 0
	v_fma_f32 v110, -v53, v109, 1.0
	v_fmac_f32_e32 v109, v110, v109
	v_div_scale_f32 v110, vcc, 2.0, v52, 2.0
	v_mul_f32_e32 v111, v110, v109
	v_fma_f32 v112, -v53, v111, v110
	v_fmac_f32_e32 v111, v112, v109
	v_fma_f32 v53, -v53, v111, v110
	v_div_fmas_f32 v53, v53, v109, v111
	v_div_fixup_f32 v52, v53, v52, 2.0
	v_sub_f32_e32 v52, 1.0, v52
	v_add_f32_e32 v52, 1.0, v52
	v_mul_f32_e32 v42, v42, v52
	v_bfe_u32 v52, v42, 16, 1
	v_add3_u32 v42, v42, v52, s31
	global_store_short_d16_hi v[48:49], v42, off
	v_or_b32_e32 v48, 17, v82
	v_mov_b32_e32 v49, v83
	v_lshlrev_b64 v[48:49], 9, v[48:49]
	v_lshl_add_u64 v[48:49], v[48:49], 0, v[50:51]
	v_lshlrev_b64 v[48:49], 1, v[48:49]
	v_lshl_add_u64 v[52:53], s[8:9], 0, v[48:49]
	s_waitcnt vmcnt(3)
	v_lshlrev_b32_e32 v42, 16, v205
	v_fmac_f32_e32 v43, v54, v42
	v_mul_f32_e32 v42, 0x3d372713, v43
	v_mul_f32_e32 v42, v43, v42
	v_fma_f32 v42, v43, v42, v43
	v_mul_f32_e32 v42, 0x3f4c422a, v42
	v_add_f32_e32 v42, v42, v42
	v_mul_f32_e32 v42, 0x3fb8aa3b, v42
	v_exp_f32_e32 v42, v42
	v_mul_f32_e32 v43, 0.5, v43
	v_add_f32_e32 v42, 1.0, v42
	v_div_scale_f32 v52, s[2:3], v42, v42, 2.0
	v_rcp_f32_e32 v53, v52
	s_nop 0
	v_fma_f32 v109, -v52, v53, 1.0
	v_fmac_f32_e32 v53, v109, v53
	v_div_scale_f32 v109, vcc, 2.0, v42, 2.0
	v_mul_f32_e32 v110, v109, v53
	v_fma_f32 v111, -v52, v110, v109
	v_fmac_f32_e32 v110, v111, v53
	v_fma_f32 v52, -v52, v110, v109
	v_div_fmas_f32 v52, v52, v53, v110
	v_div_fixup_f32 v42, v52, v42, 2.0
	v_sub_f32_e32 v42, 1.0, v42
	v_add_f32_e32 v42, 1.0, v42
	v_mul_f32_e32 v42, v43, v42
	v_bfe_u32 v43, v42, 16, 1
	v_add3_u32 v52, v42, v43, s31
	v_lshl_add_u64 v[42:43], s[28:29], 0, v[48:49]
	global_store_short_d16_hi v[42:43], v52, off
	v_or_b32_e32 v42, 18, v82
	v_mov_b32_e32 v43, v83
	v_lshlrev_b64 v[42:43], 9, v[42:43]
	v_lshl_add_u64 v[42:43], v[42:43], 0, v[50:51]
	v_lshlrev_b64 v[42:43], 1, v[42:43]
	v_lshl_add_u64 v[48:49], s[8:9], 0, v[42:43]
	v_lshl_add_u64 v[42:43], s[28:29], 0, v[42:43]
	s_waitcnt vmcnt(3)
	v_lshlrev_b32_e32 v48, 16, v206
	v_fma_f32 v44, v54, v48, v44
	v_mul_f32_e32 v48, 0x3d372713, v44
	v_mul_f32_e32 v48, v44, v48
	v_fma_f32 v48, v44, v48, v44
	v_mul_f32_e32 v48, 0x3f4c422a, v48
	v_add_f32_e32 v48, v48, v48
	v_mul_f32_e32 v48, 0x3fb8aa3b, v48
	v_exp_f32_e32 v48, v48
	v_mul_f32_e32 v44, 0.5, v44
	v_add_f32_e32 v48, 1.0, v48
	v_div_scale_f32 v49, s[2:3], v48, v48, 2.0
	v_rcp_f32_e32 v52, v49
	s_nop 0
	v_fma_f32 v53, -v49, v52, 1.0
	v_fmac_f32_e32 v52, v53, v52
	v_div_scale_f32 v53, vcc, 2.0, v48, 2.0
	v_mul_f32_e32 v109, v53, v52
	v_fma_f32 v110, -v49, v109, v53
	v_fmac_f32_e32 v109, v110, v52
	v_fma_f32 v49, -v49, v109, v53
	v_div_fmas_f32 v49, v49, v52, v109
	v_div_fixup_f32 v48, v49, v48, 2.0
	v_sub_f32_e32 v48, 1.0, v48
	v_add_f32_e32 v48, 1.0, v48
	v_mul_f32_e32 v44, v44, v48
	v_bfe_u32 v48, v44, 16, 1
	v_add3_u32 v44, v44, v48, s31
	global_store_short_d16_hi v[42:43], v44, off
	v_or_b32_e32 v42, 19, v82
	v_mov_b32_e32 v43, v83
	v_lshlrev_b64 v[42:43], 9, v[42:43]
	v_lshl_add_u64 v[42:43], v[42:43], 0, v[50:51]
	v_lshlrev_b64 v[42:43], 1, v[42:43]
	v_lshl_add_u64 v[48:49], s[8:9], 0, v[42:43]
	v_lshl_add_u64 v[42:43], s[28:29], 0, v[42:43]
	v_mfma_f32_16x16x32_bf16 v[110:113], v[38:41], v[26:29], 0
	s_waitcnt vmcnt(3)
	v_lshlrev_b32_e32 v44, 16, v207
	v_fmac_f32_e32 v45, v54, v44
	v_mul_f32_e32 v44, 0x3d372713, v45
	v_mul_f32_e32 v44, v45, v44
	v_fma_f32 v44, v45, v44, v45
	v_mul_f32_e32 v44, 0x3f4c422a, v44
	v_add_f32_e32 v44, v44, v44
	v_mul_f32_e32 v44, 0x3fb8aa3b, v44
	v_exp_f32_e32 v44, v44
	v_mul_f32_e32 v45, 0.5, v45
	v_add_f32_e32 v44, 1.0, v44
	v_div_scale_f32 v48, s[2:3], v44, v44, 2.0
	v_rcp_f32_e32 v49, v48
	s_nop 0
	v_fma_f32 v52, -v48, v49, 1.0
	v_fmac_f32_e32 v49, v52, v49
	v_div_scale_f32 v52, vcc, 2.0, v44, 2.0
	v_mul_f32_e32 v53, v52, v49
	v_fma_f32 v109, -v48, v53, v52
	v_fmac_f32_e32 v53, v109, v49
	v_fma_f32 v48, -v48, v53, v52
	v_div_fmas_f32 v48, v48, v49, v53
	v_div_fixup_f32 v44, v48, v44, 2.0
	v_sub_f32_e32 v44, 1.0, v44
	v_add_f32_e32 v44, 1.0, v44
	v_mul_f32_e32 v44, v45, v44
	v_bfe_u32 v45, v44, 16, 1
	v_add3_u32 v44, v44, v45, s31
	global_store_short_d16_hi v[42:43], v44, off
	v_mfma_f32_16x16x32_bf16 v[42:45], v[38:41], v[34:37], 0
	v_mov_b32_e32 v48, v110
	v_mov_b32_e32 v52, v112
	s_nop 4
	v_mov_b32_e32 v49, v42
	v_mov_b32_e32 v42, v111
	v_mov_b32_e32 v53, v44
	v_mov_b32_e32 v44, v113
	v_mfma_f32_16x16x32_bf16 v[110:113], v[38:41], v[22:25], 0
	v_mfma_f32_16x16x32_bf16 v[22:25], v[2:5], v[22:25], 0
	s_nop 6
	v_mov_b32_e32 v118, v110
	ds_write2_b64 v108, v[48:49], v[118:119] offset1:16
	v_mov_b32_e32 v114, v111
	v_mov_b32_e32 v48, v112
	v_mov_b32_e32 v49, v116
	v_mov_b32_e32 v116, v113
	v_mfma_f32_16x16x32_bf16 v[110:113], v[38:41], v[18:21], 0
	ds_write2_b64 v108, v[52:53], v[48:49] offset0:128 offset1:144
	v_mfma_f32_16x16x32_bf16 v[118:121], v[38:41], v[14:17], 0
	v_mfma_f32_16x16x32_bf16 v[18:21], v[2:5], v[18:21], 0
	s_nop 4
	v_mov_b32_e32 v48, v110
	s_nop 0
	v_mov_b32_e32 v49, v118
	ds_write2_b64 v108, v[48:49], v[42:43] offset0:32 offset1:64
	v_mov_b32_e32 v42, v112
	v_mov_b32_e32 v43, v120
	ds_write2_b64 v108, v[42:43], v[44:45] offset0:160 offset1:192
	v_mfma_f32_16x16x32_bf16 v[42:45], v[38:41], v[10:13], 0
	v_mov_b32_e32 v118, v111
	v_mov_b32_e32 v120, v113
	ds_write2_b64 v108, v[114:115], v[118:119] offset0:80 offset1:96
	v_mfma_f32_16x16x32_bf16 v[38:41], v[38:41], v[6:9], 0
	ds_write2_b64 v108, v[116:117], v[120:121] offset0:208 offset1:224
	s_nop 2
	v_mov_b32_e32 v48, v42
	v_mfma_f32_16x16x32_bf16 v[14:17], v[2:5], v[14:17], 0
	v_mfma_f32_16x16x32_bf16 v[10:13], v[2:5], v[10:13], 0
	s_nop 0
	v_mov_b32_e32 v49, v38
	v_mov_b32_e32 v38, v43
	ds_write2st64_b64 v99, v[48:49], v[38:39] offset0:8 offset1:9
	v_mov_b32_e32 v38, v44
	v_mov_b32_e32 v39, v40
	v_mov_b32_e32 v40, v45
	ds_write2st64_b64 v99, v[38:39], v[40:41] offset0:10 offset1:11
	s_waitcnt lgkmcnt(0)
; __device__ __forceinline__ void s5_pass2_item(PP p, unsigned char* shm, int item, int l) {
;     ...
;         __syncthreads();
; #pragma unroll
;         for (int t = 0; t < 16; ++t) { s5_rec(q, *(const f32x2*)(buL + (t * 64 + lane) * 2), x); xs[t * 132 + lane] = x.x; xs[t * 132 + 64 + lane] = x.y; }
	ds_read_b64 v[140:141], v90 offset:4096
	ds_read_b64 v[142:143], v90 offset:4608
	ds_read_b64 v[144:145], v90 offset:5120
	ds_read_b64 v[146:147], v90 offset:5632
	ds_read_b64 v[148:149], v90 offset:6144
	ds_read_b64 v[150:151], v90 offset:6656
	ds_read_b64 v[152:153], v90 offset:7168
	ds_read_b64 v[154:155], v90 offset:7680
	v_xor_b32_e32 v40, 0x80000000, v47
	v_mov_b32_e32 v41, v46
	v_pk_mul_f32 v[40:41], v[0:1], v[40:41] op_sel_hi:[0,1]
	v_pk_fma_f32 v[40:41], v[84:85], v[46:47], v[40:41] op_sel_hi:[0,1,1]
	s_waitcnt lgkmcnt(7)
	v_pk_add_f32 v[38:39], v[40:41], v[140:141]
	ds_write2st64_b32 v98, v38, v39 offset1:1
	v_xor_b32_e32 v42, 0x80000000, v39
	v_mov_b32_e32 v43, v38
	v_pk_mul_f32 v[42:43], v[0:1], v[42:43] op_sel_hi:[0,1]
	v_pk_fma_f32 v[38:39], v[84:85], v[38:39], v[42:43] op_sel_hi:[0,1,1]
	s_waitcnt lgkmcnt(7)
	v_pk_add_f32 v[38:39], v[142:143], v[38:39]
	ds_write2_b32 v98, v38, v39 offset0:132 offset1:196
	v_xor_b32_e32 v42, 0x80000000, v39
	v_mov_b32_e32 v43, v38
	v_pk_mul_f32 v[42:43], v[0:1], v[42:43] op_sel_hi:[0,1]
	v_pk_fma_f32 v[38:39], v[84:85], v[38:39], v[42:43] op_sel_hi:[0,1,1]
	s_waitcnt lgkmcnt(7)
	v_pk_add_f32 v[38:39], v[144:145], v[38:39]
	ds_write2st64_b32 v78, v38, v39 offset0:4 offset1:5
	v_xor_b32_e32 v42, 0x80000000, v39
	v_mov_b32_e32 v43, v38
	v_pk_mul_f32 v[42:43], v[0:1], v[42:43] op_sel_hi:[0,1]
	v_pk_fma_f32 v[38:39], v[84:85], v[38:39], v[42:43] op_sel_hi:[0,1,1]
	s_waitcnt lgkmcnt(7)
	v_pk_add_f32 v[38:39], v[146:147], v[38:39]
	ds_write2st64_b32 v79, v38, v39 offset0:6 offset1:7
	v_xor_b32_e32 v42, 0x80000000, v39
	v_mov_b32_e32 v43, v38
	v_pk_mul_f32 v[42:43], v[0:1], v[42:43] op_sel_hi:[0,1]
	v_pk_fma_f32 v[38:39], v[84:85], v[38:39], v[42:43] op_sel_hi:[0,1,1]
	s_waitcnt lgkmcnt(7)
	v_pk_add_f32 v[38:39], v[148:149], v[38:39]
	ds_write2st64_b32 v80, v38, v39 offset0:8 offset1:9
	v_xor_b32_e32 v42, 0x80000000, v39
	v_mov_b32_e32 v43, v38
	v_pk_mul_f32 v[42:43], v[0:1], v[42:43] op_sel_hi:[0,1]
	v_pk_fma_f32 v[38:39], v[84:85], v[38:39], v[42:43] op_sel_hi:[0,1,1]
	s_waitcnt lgkmcnt(7)
	v_pk_add_f32 v[38:39], v[150:151], v[38:39]
	ds_write2st64_b32 v81, v38, v39 offset0:10 offset1:11
	v_xor_b32_e32 v42, 0x80000000, v39
	v_mov_b32_e32 v43, v38
	v_pk_mul_f32 v[42:43], v[0:1], v[42:43] op_sel_hi:[0,1]
	v_pk_fma_f32 v[38:39], v[84:85], v[38:39], v[42:43] op_sel_hi:[0,1,1]
	s_waitcnt lgkmcnt(7)
	v_pk_add_f32 v[38:39], v[152:153], v[38:39]
	ds_write2st64_b32 v86, v38, v39 offset0:12 offset1:13
	v_xor_b32_e32 v42, 0x80000000, v39
	v_mov_b32_e32 v43, v38
	v_pk_mul_f32 v[42:43], v[0:1], v[42:43] op_sel_hi:[0,1]
	v_pk_fma_f32 v[38:39], v[84:85], v[38:39], v[42:43] op_sel_hi:[0,1,1]
	s_waitcnt lgkmcnt(7)
	v_pk_add_f32 v[38:39], v[154:155], v[38:39]
	ds_write2st64_b32 v87, v38, v39 offset0:14 offset1:15
	ds_read_b64 v[140:141], v90 offset:8192
	ds_read_b64 v[142:143], v90 offset:8704
	ds_read_b64 v[144:145], v90 offset:9216
	ds_read_b64 v[146:147], v90 offset:9728
	ds_read_b64 v[148:149], v90 offset:10240
	ds_read_b64 v[150:151], v90 offset:10752
	ds_read_b64 v[152:153], v90 offset:11264
	ds_read_b64 v[154:155], v90 offset:11776
	v_xor_b32_e32 v42, 0x80000000, v39
	v_mov_b32_e32 v43, v38
	v_pk_mul_f32 v[42:43], v[0:1], v[42:43] op_sel_hi:[0,1]
	v_pk_fma_f32 v[38:39], v[84:85], v[38:39], v[42:43] op_sel_hi:[0,1,1]
	s_waitcnt lgkmcnt(7)
	v_pk_add_f32 v[38:39], v[140:141], v[38:39]
	ds_write2st64_b32 v100, v38, v39 offset0:16 offset1:17
	v_xor_b32_e32 v42, 0x80000000, v39
	v_mov_b32_e32 v43, v38
	v_pk_mul_f32 v[42:43], v[0:1], v[42:43] op_sel_hi:[0,1]
	v_pk_fma_f32 v[38:39], v[84:85], v[38:39], v[42:43] op_sel_hi:[0,1,1]
	s_waitcnt lgkmcnt(7)
	v_pk_add_f32 v[38:39], v[142:143], v[38:39]
	ds_write2st64_b32 v101, v38, v39 offset0:18 offset1:19
	v_xor_b32_e32 v42, 0x80000000, v39
	v_mov_b32_e32 v43, v38
	v_pk_mul_f32 v[42:43], v[0:1], v[42:43] op_sel_hi:[0,1]
	v_pk_fma_f32 v[38:39], v[84:85], v[38:39], v[42:43] op_sel_hi:[0,1,1]
	s_waitcnt lgkmcnt(7)
	v_pk_add_f32 v[38:39], v[144:145], v[38:39]
	ds_write2st64_b32 v102, v38, v39 offset0:20 offset1:21
	v_xor_b32_e32 v42, 0x80000000, v39
	v_mov_b32_e32 v43, v38
	v_pk_mul_f32 v[42:43], v[0:1], v[42:43] op_sel_hi:[0,1]
	v_pk_fma_f32 v[38:39], v[84:85], v[38:39], v[42:43] op_sel_hi:[0,1,1]
	s_waitcnt lgkmcnt(7)
	v_pk_add_f32 v[38:39], v[146:147], v[38:39]
	ds_write2st64_b32 v103, v38, v39 offset0:22 offset1:23
	v_xor_b32_e32 v42, 0x80000000, v39
	v_mov_b32_e32 v43, v38
	v_pk_mul_f32 v[42:43], v[0:1], v[42:43] op_sel_hi:[0,1]
	v_pk_fma_f32 v[38:39], v[84:85], v[38:39], v[42:43] op_sel_hi:[0,1,1]
	s_waitcnt lgkmcnt(7)
	v_pk_add_f32 v[38:39], v[148:149], v[38:39]
	ds_write2st64_b32 v104, v38, v39 offset0:24 offset1:25
	v_xor_b32_e32 v42, 0x80000000, v39
	v_mov_b32_e32 v43, v38
	v_pk_mul_f32 v[42:43], v[0:1], v[42:43] op_sel_hi:[0,1]
	v_pk_fma_f32 v[38:39], v[84:85], v[38:39], v[42:43] op_sel_hi:[0,1,1]
	s_waitcnt lgkmcnt(7)
	v_pk_add_f32 v[38:39], v[150:151], v[38:39]
	ds_write2st64_b32 v105, v38, v39 offset0:26 offset1:27
	v_xor_b32_e32 v42, 0x80000000, v39
	v_mov_b32_e32 v43, v38
	v_pk_mul_f32 v[42:43], v[0:1], v[42:43] op_sel_hi:[0,1]
	v_pk_fma_f32 v[38:39], v[84:85], v[38:39], v[42:43] op_sel_hi:[0,1,1]
	s_waitcnt lgkmcnt(7)
	v_pk_add_f32 v[38:39], v[152:153], v[38:39]
	ds_write2st64_b32 v106, v38, v39 offset0:28 offset1:29
	v_xor_b32_e32 v42, 0x80000000, v39
	v_mov_b32_e32 v43, v38
	v_pk_mul_f32 v[42:43], v[0:1], v[42:43] op_sel_hi:[0,1]
	v_pk_fma_f32 v[38:39], v[84:85], v[38:39], v[42:43] op_sel_hi:[0,1,1]
	s_waitcnt lgkmcnt(7)
	v_pk_add_f32 v[38:39], v[154:155], v[38:39]
	ds_write2st64_b32 v107, v38, v39 offset0:30 offset1:31
	s_waitcnt lgkmcnt(0)
; __device__ __forceinline__ float bf2f(bf16_t v) { return __uint_as_float(((unsigned)v) << 16); }
; __device__ __forceinline__ bf16_t f2bf(float f) { unsigned u = __float_as_uint(f); u += 0x7FFFu + ((u >> 16) & 1u); return (bf16_t)(u >> 16); }
; __device__ __forceinline__ void s5_pass2_item(PP p, unsigned char* shm, int item, int l) {
;     ...
;         for (int t = 0; t < 16; ++t) { s5_rec(q, *(const f32x2*)(buL + (t * 64 + lane) * 2), x); xs[t * 132 + lane] = x.x; xs[t * 132 + 64 + lane] = x.y; }
;         __syncthreads();
;         f32x4 y0 = (f32x4){0.f, 0.f, 0.f, 0.f}, y1 = y0;
;         const f32x4* xrow = (const f32x4*)(xs + cc * 132 + quad * 32);
; #pragma unroll
;         for (int i = 0; i < 8; ++i) { const f32x4 xv = xrow[i];
;             y0 = __builtin_amdgcn_mfma_f32_16x16x4f32(xv[0], cmr[4 * i + 0], y0, 0, 0, 0);
;             y1 = __builtin_amdgcn_mfma_f32_16x16x4f32(xv[1], cmr[4 * i + 1], y1, 0, 0, 0);
;             y0 = __builtin_amdgcn_mfma_f32_16x16x4f32(xv[2], cmr[4 * i + 2], y0, 0, 0, 0);
;             y1 = __builtin_amdgcn_mfma_f32_16x16x4f32(xv[3], cmr[4 * i + 3], y1, 0, 0, 0); }
;         const f32x4 y = y0 + y1;
; #pragma unroll
;         for (int r = 0; r < 4; ++r) { const int tl = sc * 16 + quad * 4 + r;
;             const float v = y[r] + dsk * bf2f(proj[PJ_UA + (row0 + tl) * 512 + g * 16 + cc]);
;             const float z = 0.7978845608028654f * (v + 0.044715f * v * v * v);
;             const float th = 1.0f - 2.0f / (__expf(2.0f * z) + 1.0f);
;             Gout[(row0 + tl) * 512 + g * 16 + cc] = f2bf(0.5f * v * (1.0f + th)); }
	v_or_b32_e32 v216, 32, v82
	v_mov_b32_e32 v217, v83
	v_lshlrev_b64 v[216:217], 9, v[216:217]
	v_lshl_add_u64 v[216:217], v[216:217], 0, v[50:51]
	v_lshlrev_b64 v[216:217], 1, v[216:217]
	v_lshl_add_u64 v[216:217], s[8:9], 0, v[216:217]
	global_load_ushort v208, v[216:217], off
	global_load_ushort v209, v[216:217], off offset:1024
	global_load_ushort v210, v[216:217], off offset:2048
	global_load_ushort v211, v[216:217], off offset:3072
	ds_read_b128 v[40:43], v89
	ds_read_b128 v[44:47], v89 offset:16
	ds_read_b128 v[110:113], v89 offset:32
	ds_read_b128 v[114:117], v89 offset:48
	s_waitcnt lgkmcnt(3)
	v_mfma_f32_16x16x4_f32 v[118:121], v40, v97, 0
	v_mfma_f32_16x16x4_f32 v[122:125], v41, v96, 0
	v_mfma_f32_16x16x4_f32 v[118:121], v42, v95, v[118:121]
	v_mfma_f32_16x16x4_f32 v[40:43], v43, v94, v[122:125]
	s_waitcnt lgkmcnt(2)
	v_mfma_f32_16x16x4_f32 v[118:121], v44, v93, v[118:121]
	v_mfma_f32_16x16x4_f32 v[40:43], v45, v92, v[40:43]
	v_mfma_f32_16x16x4_f32 v[118:121], v46, v91, v[118:121]
	v_mfma_f32_16x16x4_f32 v[40:43], v47, v88, v[40:43]
	s_waitcnt lgkmcnt(1)
	v_mfma_f32_16x16x4_f32 v[44:47], v110, v85, v[118:121]
	v_mfma_f32_16x16x4_f32 v[40:43], v111, v55, v[40:43]
	v_mfma_f32_16x16x4_f32 v[44:47], v112, v56, v[44:47]
	v_mfma_f32_16x16x4_f32 v[40:43], v113, v57, v[40:43]
	ds_read_b128 v[110:113], v89 offset:64
	s_waitcnt lgkmcnt(1)
	v_mfma_f32_16x16x4_f32 v[44:47], v114, v58, v[44:47]
	v_mfma_f32_16x16x4_f32 v[40:43], v115, v59, v[40:43]
	v_mfma_f32_16x16x4_f32 v[44:47], v116, v60, v[44:47]
	v_mfma_f32_16x16x4_f32 v[40:43], v117, v61, v[40:43]
	s_waitcnt lgkmcnt(0)
	v_mfma_f32_16x16x4_f32 v[44:47], v110, v62, v[44:47]
	v_mfma_f32_16x16x4_f32 v[40:43], v111, v63, v[40:43]
	v_mfma_f32_16x16x4_f32 v[44:47], v112, v64, v[44:47]
	v_mfma_f32_16x16x4_f32 v[40:43], v113, v65, v[40:43]
	ds_read_b128 v[110:113], v89 offset:80
	s_waitcnt lgkmcnt(0)
	v_mfma_f32_16x16x4_f32 v[44:47], v110, v66, v[44:47]
	v_mfma_f32_16x16x4_f32 v[40:43], v111, v67, v[40:43]
	v_mfma_f32_16x16x4_f32 v[44:47], v112, v68, v[44:47]
	v_mfma_f32_16x16x4_f32 v[40:43], v113, v69, v[40:43]
	ds_read_b128 v[110:113], v89 offset:96
	s_waitcnt lgkmcnt(0)
	v_mfma_f32_16x16x4_f32 v[44:47], v110, v70, v[44:47]
	v_mfma_f32_16x16x4_f32 v[40:43], v111, v71, v[40:43]
	v_mfma_f32_16x16x4_f32 v[44:47], v112, v72, v[44:47]
	v_mfma_f32_16x16x4_f32 v[40:43], v113, v73, v[40:43]
	ds_read_b128 v[110:113], v89 offset:112
	s_waitcnt lgkmcnt(0)
	v_mfma_f32_16x16x4_f32 v[44:47], v110, v74, v[44:47]
	v_mfma_f32_16x16x4_f32 v[40:43], v111, v75, v[40:43]
	v_mfma_f32_16x16x4_f32 v[44:47], v112, v76, v[44:47]
	v_mfma_f32_16x16x4_f32 v[40:43], v113, v77, v[40:43]
	s_nop 9
	v_pk_add_f32 v[40:41], v[44:45], v[40:41]
	v_or_b32_e32 v44, 32, v82
	v_mov_b32_e32 v45, v83
	v_lshlrev_b64 v[44:45], 9, v[44:45]
	v_lshl_add_u64 v[44:45], v[44:45], 0, v[50:51]
	v_lshlrev_b64 v[44:45], 1, v[44:45]
	v_pk_add_f32 v[42:43], v[46:47], v[42:43]
	v_lshl_add_u64 v[46:47], s[8:9], 0, v[44:45]
	v_lshl_add_u64 v[44:45], s[28:29], 0, v[44:45]
	s_waitcnt vmcnt(3)
	v_lshlrev_b32_e32 v46, 16, v208
	v_fma_f32 v40, v54, v46, v40
	v_mul_f32_e32 v46, 0x3d372713, v40
	v_mul_f32_e32 v46, v40, v46
	v_fma_f32 v46, v40, v46, v40
	v_mul_f32_e32 v46, 0x3f4c422a, v46
	v_add_f32_e32 v46, v46, v46
	v_mul_f32_e32 v46, 0x3fb8aa3b, v46
	v_exp_f32_e32 v46, v46
	v_mul_f32_e32 v40, 0.5, v40
	v_add_f32_e32 v46, 1.0, v46
	v_div_scale_f32 v47, s[2:3], v46, v46, 2.0
	v_rcp_f32_e32 v48, v47
	s_nop 0
	v_fma_f32 v49, -v47, v48, 1.0
	v_fmac_f32_e32 v48, v49, v48
	v_div_scale_f32 v49, vcc, 2.0, v46, 2.0
	v_mul_f32_e32 v52, v49, v48
	v_fma_f32 v53, -v47, v52, v49
	v_fmac_f32_e32 v52, v53, v48
	v_fma_f32 v47, -v47, v52, v49
	v_div_fmas_f32 v47, v47, v48, v52
	v_div_fixup_f32 v46, v47, v46, 2.0
	v_sub_f32_e32 v46, 1.0, v46
	v_add_f32_e32 v46, 1.0, v46
	v_mul_f32_e32 v40, v40, v46
	v_bfe_u32 v46, v40, 16, 1
	v_add3_u32 v40, v40, v46, s31
	global_store_short_d16_hi v[44:45], v40, off
	v_or_b32_e32 v44, 33, v82
	v_mov_b32_e32 v45, v83
	v_lshlrev_b64 v[44:45], 9, v[44:45]
	v_lshl_add_u64 v[44:45], v[44:45], 0, v[50:51]
	v_lshlrev_b64 v[44:45], 1, v[44:45]
	v_lshl_add_u64 v[46:47], s[8:9], 0, v[44:45]
	s_waitcnt vmcnt(3)
	v_lshlrev_b32_e32 v40, 16, v209
	v_fmac_f32_e32 v41, v54, v40
	v_mul_f32_e32 v40, 0x3d372713, v41
	v_mul_f32_e32 v40, v41, v40
	v_fma_f32 v40, v41, v40, v41
	v_mul_f32_e32 v40, 0x3f4c422a, v40
	v_add_f32_e32 v40, v40, v40
	v_mul_f32_e32 v40, 0x3fb8aa3b, v40
	v_exp_f32_e32 v40, v40
	v_mul_f32_e32 v41, 0.5, v41
	v_add_f32_e32 v40, 1.0, v40
	v_div_scale_f32 v46, s[2:3], v40, v40, 2.0
	v_rcp_f32_e32 v47, v46
	s_nop 0
	v_fma_f32 v48, -v46, v47, 1.0
	v_fmac_f32_e32 v47, v48, v47
	v_div_scale_f32 v48, vcc, 2.0, v40, 2.0
	v_mul_f32_e32 v49, v48, v47
	v_fma_f32 v52, -v46, v49, v48
	v_fmac_f32_e32 v49, v52, v47
	v_fma_f32 v46, -v46, v49, v48
	v_div_fmas_f32 v46, v46, v47, v49
	v_div_fixup_f32 v40, v46, v40, 2.0
	v_sub_f32_e32 v40, 1.0, v40
	v_add_f32_e32 v40, 1.0, v40
	v_mul_f32_e32 v40, v41, v40
	v_bfe_u32 v41, v40, 16, 1
	v_add3_u32 v46, v40, v41, s31
	v_lshl_add_u64 v[40:41], s[28:29], 0, v[44:45]
	global_store_short_d16_hi v[40:41], v46, off
	v_or_b32_e32 v40, 34, v82
	v_mov_b32_e32 v41, v83
	v_lshlrev_b64 v[40:41], 9, v[40:41]
	v_lshl_add_u64 v[40:41], v[40:41], 0, v[50:51]
	v_lshlrev_b64 v[40:41], 1, v[40:41]
	v_lshl_add_u64 v[44:45], s[8:9], 0, v[40:41]
	v_lshl_add_u64 v[40:41], s[28:29], 0, v[40:41]
	s_waitcnt vmcnt(3)
; __device__ __forceinline__ float bf2f(bf16_t v) { return __uint_as_float(((unsigned)v) << 16); }
; __device__ __forceinline__ bf16_t f2bf(float f) { unsigned u = __float_as_uint(f); u += 0x7FFFu + ((u >> 16) & 1u); return (bf16_t)(u >> 16); }
; __device__ __forceinline__ void s5_pass2_item(PP p, unsigned char* shm, int item, int l) {
;     ...
;     for (int sc = 0; sc < 4; ++sc) {
;         s5_bu16(f, uf[sc], buL, lane);
;         __syncthreads();
; #pragma unroll
;         for (int t = 0; t < 16; ++t) { s5_rec(q, *(const f32x2*)(buL + (t * 64 + lane) * 2), x); xs[t * 132 + lane] = x.x; xs[t * 132 + 64 + lane] = x.y; }
;         __syncthreads();
;         f32x4 y0 = (f32x4){0.f, 0.f, 0.f, 0.f}, y1 = y0;
;         const f32x4* xrow = (const f32x4*)(xs + cc * 132 + quad * 32);
; #pragma unroll
;         for (int i = 0; i < 8; ++i) { const f32x4 xv = xrow[i];
;             y0 = __builtin_amdgcn_mfma_f32_16x16x4f32(xv[0], cmr[4 * i + 0], y0, 0, 0, 0);
;             y1 = __builtin_amdgcn_mfma_f32_16x16x4f32(xv[1], cmr[4 * i + 1], y1, 0, 0, 0);
;             y0 = __builtin_amdgcn_mfma_f32_16x16x4f32(xv[2], cmr[4 * i + 2], y0, 0, 0, 0);
;             y1 = __builtin_amdgcn_mfma_f32_16x16x4f32(xv[3], cmr[4 * i + 3], y1, 0, 0, 0); }
;         const f32x4 y = y0 + y1;
; #pragma unroll
;         for (int r = 0; r < 4; ++r) { const int tl = sc * 16 + quad * 4 + r;
;             const float v = y[r] + dsk * bf2f(proj[PJ_UA + (row0 + tl) * 512 + g * 16 + cc]);
;             const float z = 0.7978845608028654f * (v + 0.044715f * v * v * v);
;             const float th = 1.0f - 2.0f / (__expf(2.0f * z) + 1.0f);
;             Gout[(row0 + tl) * 512 + g * 16 + cc] = f2bf(0.5f * v * (1.0f + th)); }
;         __syncthreads();
	v_lshlrev_b32_e32 v44, 16, v210
	v_fma_f32 v42, v54, v44, v42
	v_mul_f32_e32 v44, 0x3d372713, v42
	v_mul_f32_e32 v44, v42, v44
	v_fma_f32 v44, v42, v44, v42
	v_mul_f32_e32 v44, 0x3f4c422a, v44
	v_add_f32_e32 v44, v44, v44
	v_mul_f32_e32 v44, 0x3fb8aa3b, v44
	v_exp_f32_e32 v44, v44
	v_mul_f32_e32 v42, 0.5, v42
	v_add_f32_e32 v44, 1.0, v44
	v_div_scale_f32 v45, s[2:3], v44, v44, 2.0
	v_rcp_f32_e32 v46, v45
	s_nop 0
	v_fma_f32 v47, -v45, v46, 1.0
	v_fmac_f32_e32 v46, v47, v46
	v_div_scale_f32 v47, vcc, 2.0, v44, 2.0
	v_mul_f32_e32 v48, v47, v46
	v_fma_f32 v49, -v45, v48, v47
	v_fmac_f32_e32 v48, v49, v46
	v_fma_f32 v45, -v45, v48, v47
	v_div_fmas_f32 v45, v45, v46, v48
	v_div_fixup_f32 v44, v45, v44, 2.0
	v_sub_f32_e32 v44, 1.0, v44
	v_add_f32_e32 v44, 1.0, v44
	v_mul_f32_e32 v42, v42, v44
	v_bfe_u32 v44, v42, 16, 1
	v_add3_u32 v42, v42, v44, s31
	global_store_short_d16_hi v[40:41], v42, off
	v_or_b32_e32 v40, 35, v82
	v_mov_b32_e32 v41, v83
	v_lshlrev_b64 v[40:41], 9, v[40:41]
	v_lshl_add_u64 v[40:41], v[40:41], 0, v[50:51]
	v_lshlrev_b64 v[40:41], 1, v[40:41]
	v_lshl_add_u64 v[44:45], s[8:9], 0, v[40:41]
	v_lshl_add_u64 v[40:41], s[28:29], 0, v[40:41]
	s_waitcnt vmcnt(3)
	v_lshlrev_b32_e32 v42, 16, v211
	v_fmac_f32_e32 v43, v54, v42
	v_mul_f32_e32 v42, 0x3d372713, v43
	v_mul_f32_e32 v42, v43, v42
	v_fma_f32 v42, v43, v42, v43
	v_mul_f32_e32 v42, 0x3f4c422a, v42
	v_add_f32_e32 v42, v42, v42
	v_mul_f32_e32 v42, 0x3fb8aa3b, v42
	v_exp_f32_e32 v42, v42
	v_mul_f32_e32 v43, 0.5, v43
	v_add_f32_e32 v42, 1.0, v42
	v_div_scale_f32 v44, s[2:3], v42, v42, 2.0
	v_rcp_f32_e32 v45, v44
	s_nop 0
	v_fma_f32 v46, -v44, v45, 1.0
	v_fmac_f32_e32 v45, v46, v45
	v_div_scale_f32 v46, vcc, 2.0, v42, 2.0
	v_mul_f32_e32 v47, v46, v45
	v_fma_f32 v48, -v44, v47, v46
	v_fmac_f32_e32 v47, v48, v45
	v_fma_f32 v44, -v44, v47, v46
	v_div_fmas_f32 v44, v44, v45, v47
	v_div_fixup_f32 v42, v44, v42, 2.0
	v_sub_f32_e32 v42, 1.0, v42
	v_add_f32_e32 v42, 1.0, v42
	v_mul_f32_e32 v42, v43, v42
	v_bfe_u32 v43, v42, 16, 1
	v_add3_u32 v42, v42, v43, s31
	global_store_short_d16_hi v[40:41], v42, off
	v_mfma_f32_16x16x32_bf16 v[40:43], v[2:5], v[26:29], 0
	v_mfma_f32_16x16x32_bf16 v[26:29], v[2:5], v[34:37], 0
	v_mfma_f32_16x16x32_bf16 v[2:5], v[2:5], v[6:9], 0
	s_nop 4
	v_mov_b32_e32 v34, v40
	s_nop 0
	v_mov_b32_e32 v35, v26
	v_mov_b32_e32 v26, v41
	v_mov_b32_e32 v36, v42
	v_mov_b32_e32 v37, v28
	v_mov_b32_e32 v40, v22
	v_mov_b32_e32 v41, v30
	v_mov_b32_e32 v30, v23
	v_mov_b32_e32 v22, v24
	v_mov_b32_e32 v23, v32
	ds_write2_b64 v108, v[36:37], v[22:23] offset0:128 offset1:144
	v_mov_b32_e32 v23, v14
	v_mov_b32_e32 v14, v19
	v_mov_b32_e32 v6, v10
	v_mov_b32_e32 v7, v2
	v_mov_b32_e32 v2, v11
	v_mov_b32_e32 v28, v43
	v_mov_b32_e32 v32, v25
	v_mov_b32_e32 v22, v18
	ds_write2_b64 v108, v[30:31], v[14:15] offset0:80 offset1:96
	v_mov_b32_e32 v14, v20
	v_mov_b32_e32 v15, v16
	v_mov_b32_e32 v16, v21
	ds_write2st64_b64 v99, v[6:7], v[2:3] offset0:8 offset1:9
	v_mov_b32_e32 v2, v12
	v_mov_b32_e32 v3, v4
	v_mov_b32_e32 v4, v13
	ds_write2_b64 v108, v[34:35], v[40:41] offset1:16
	ds_write2_b64 v108, v[22:23], v[26:27] offset0:32 offset1:64
	ds_write2_b64 v108, v[14:15], v[28:29] offset0:160 offset1:192
	ds_write2_b64 v108, v[32:33], v[16:17] offset0:208 offset1:224
	ds_write2st64_b64 v99, v[2:3], v[4:5] offset0:10 offset1:11
	s_waitcnt lgkmcnt(0)
	ds_read_b64 v[140:141], v90 offset:4096
	ds_read_b64 v[142:143], v90 offset:4608
	ds_read_b64 v[144:145], v90 offset:5120
	ds_read_b64 v[146:147], v90 offset:5632
	ds_read_b64 v[148:149], v90 offset:6144
	ds_read_b64 v[150:151], v90 offset:6656
	ds_read_b64 v[152:153], v90 offset:7168
	ds_read_b64 v[154:155], v90 offset:7680
	v_xor_b32_e32 v4, 0x80000000, v39
	v_mov_b32_e32 v5, v38
	v_pk_mul_f32 v[4:5], v[0:1], v[4:5] op_sel_hi:[0,1]
	v_pk_fma_f32 v[4:5], v[84:85], v[38:39], v[4:5] op_sel_hi:[0,1,1]
	s_waitcnt lgkmcnt(7)
	v_pk_add_f32 v[2:3], v[4:5], v[140:141]
	ds_write2st64_b32 v98, v2, v3 offset1:1
	v_xor_b32_e32 v6, 0x80000000, v3
	v_mov_b32_e32 v7, v2
	v_pk_mul_f32 v[6:7], v[0:1], v[6:7] op_sel_hi:[0,1]
	v_pk_fma_f32 v[2:3], v[84:85], v[2:3], v[6:7] op_sel_hi:[0,1,1]
	s_waitcnt lgkmcnt(7)
	v_pk_add_f32 v[2:3], v[142:143], v[2:3]
	ds_write2_b32 v98, v2, v3 offset0:132 offset1:196
	v_xor_b32_e32 v6, 0x80000000, v3
	v_mov_b32_e32 v7, v2
	v_pk_mul_f32 v[6:7], v[0:1], v[6:7] op_sel_hi:[0,1]
	v_pk_fma_f32 v[2:3], v[84:85], v[2:3], v[6:7] op_sel_hi:[0,1,1]
	s_waitcnt lgkmcnt(7)
	v_pk_add_f32 v[2:3], v[144:145], v[2:3]
	ds_write2st64_b32 v78, v2, v3 offset0:4 offset1:5
	v_xor_b32_e32 v6, 0x80000000, v3
	v_mov_b32_e32 v7, v2
	v_pk_mul_f32 v[6:7], v[0:1], v[6:7] op_sel_hi:[0,1]
	v_pk_fma_f32 v[2:3], v[84:85], v[2:3], v[6:7] op_sel_hi:[0,1,1]
	s_waitcnt lgkmcnt(7)
	v_pk_add_f32 v[2:3], v[146:147], v[2:3]
	ds_write2st64_b32 v79, v2, v3 offset0:6 offset1:7
	v_xor_b32_e32 v6, 0x80000000, v3
	v_mov_b32_e32 v7, v2
	v_pk_mul_f32 v[6:7], v[0:1], v[6:7] op_sel_hi:[0,1]
	v_pk_fma_f32 v[2:3], v[84:85], v[2:3], v[6:7] op_sel_hi:[0,1,1]
	s_waitcnt lgkmcnt(7)
	v_pk_add_f32 v[2:3], v[148:149], v[2:3]
	ds_write2st64_b32 v80, v2, v3 offset0:8 offset1:9
	v_xor_b32_e32 v6, 0x80000000, v3
	v_mov_b32_e32 v7, v2
	v_pk_mul_f32 v[6:7], v[0:1], v[6:7] op_sel_hi:[0,1]
	v_pk_fma_f32 v[2:3], v[84:85], v[2:3], v[6:7] op_sel_hi:[0,1,1]
	s_waitcnt lgkmcnt(7)
	v_pk_add_f32 v[2:3], v[150:151], v[2:3]
	ds_write2st64_b32 v81, v2, v3 offset0:10 offset1:11
	v_xor_b32_e32 v6, 0x80000000, v3
	v_mov_b32_e32 v7, v2
	v_pk_mul_f32 v[6:7], v[0:1], v[6:7] op_sel_hi:[0,1]
	v_pk_fma_f32 v[2:3], v[84:85], v[2:3], v[6:7] op_sel_hi:[0,1,1]
	s_waitcnt lgkmcnt(7)
; __device__ __forceinline__ void s5_pass2_item(PP p, unsigned char* shm, int item, int l) {
;     ...
;         __syncthreads();
; #pragma unroll
;         for (int t = 0; t < 16; ++t) { s5_rec(q, *(const f32x2*)(buL + (t * 64 + lane) * 2), x); xs[t * 132 + lane] = x.x; xs[t * 132 + 64 + lane] = x.y; }
;         __syncthreads();
;         f32x4 y0 = (f32x4){0.f, 0.f, 0.f, 0.f}, y1 = y0;
;         const f32x4* xrow = (const f32x4*)(xs + cc * 132 + quad * 32);
; #pragma unroll
;         for (int i = 0; i < 8; ++i) { const f32x4 xv = xrow[i];
;             y0 = __builtin_amdgcn_mfma_f32_16x16x4f32(xv[0], cmr[4 * i + 0], y0, 0, 0, 0);
;             y1 = __builtin_amdgcn_mfma_f32_16x16x4f32(xv[1], cmr[4 * i + 1], y1, 0, 0, 0);
;             y0 = __builtin_amdgcn_mfma_f32_16x16x4f32(xv[2], cmr[4 * i + 2], y0, 0, 0, 0);
;             y1 = __builtin_amdgcn_mfma_f32_16x16x4f32(xv[3], cmr[4 * i + 3], y1, 0, 0, 0); }
	v_pk_add_f32 v[2:3], v[152:153], v[2:3]
	ds_write2st64_b32 v86, v2, v3 offset0:12 offset1:13
	v_xor_b32_e32 v6, 0x80000000, v3
	v_mov_b32_e32 v7, v2
	v_pk_mul_f32 v[6:7], v[0:1], v[6:7] op_sel_hi:[0,1]
	v_pk_fma_f32 v[2:3], v[84:85], v[2:3], v[6:7] op_sel_hi:[0,1,1]
	s_waitcnt lgkmcnt(7)
	v_pk_add_f32 v[2:3], v[154:155], v[2:3]
	ds_write2st64_b32 v87, v2, v3 offset0:14 offset1:15
	ds_read_b64 v[140:141], v90 offset:8192
	ds_read_b64 v[142:143], v90 offset:8704
	ds_read_b64 v[144:145], v90 offset:9216
	ds_read_b64 v[146:147], v90 offset:9728
	ds_read_b64 v[148:149], v90 offset:10240
	ds_read_b64 v[150:151], v90 offset:10752
	ds_read_b64 v[152:153], v90 offset:11264
	ds_read_b64 v[154:155], v90 offset:11776
	v_xor_b32_e32 v6, 0x80000000, v3
	v_mov_b32_e32 v7, v2
	v_pk_mul_f32 v[6:7], v[0:1], v[6:7] op_sel_hi:[0,1]
	v_pk_fma_f32 v[2:3], v[84:85], v[2:3], v[6:7] op_sel_hi:[0,1,1]
	s_waitcnt lgkmcnt(7)
	v_pk_add_f32 v[2:3], v[140:141], v[2:3]
	ds_write2st64_b32 v100, v2, v3 offset0:16 offset1:17
	v_xor_b32_e32 v6, 0x80000000, v3
	v_mov_b32_e32 v7, v2
	v_pk_mul_f32 v[6:7], v[0:1], v[6:7] op_sel_hi:[0,1]
	v_pk_fma_f32 v[2:3], v[84:85], v[2:3], v[6:7] op_sel_hi:[0,1,1]
	s_waitcnt lgkmcnt(7)
	v_pk_add_f32 v[2:3], v[142:143], v[2:3]
	ds_write2st64_b32 v101, v2, v3 offset0:18 offset1:19
	v_xor_b32_e32 v6, 0x80000000, v3
	v_mov_b32_e32 v7, v2
	v_pk_mul_f32 v[6:7], v[0:1], v[6:7] op_sel_hi:[0,1]
	v_pk_fma_f32 v[2:3], v[84:85], v[2:3], v[6:7] op_sel_hi:[0,1,1]
	s_waitcnt lgkmcnt(7)
	v_pk_add_f32 v[2:3], v[144:145], v[2:3]
	ds_write2st64_b32 v102, v2, v3 offset0:20 offset1:21
	v_xor_b32_e32 v6, 0x80000000, v3
	v_mov_b32_e32 v7, v2
	v_pk_mul_f32 v[6:7], v[0:1], v[6:7] op_sel_hi:[0,1]
	v_pk_fma_f32 v[2:3], v[84:85], v[2:3], v[6:7] op_sel_hi:[0,1,1]
	s_waitcnt lgkmcnt(7)
	v_pk_add_f32 v[2:3], v[146:147], v[2:3]
	ds_write2st64_b32 v103, v2, v3 offset0:22 offset1:23
	v_xor_b32_e32 v6, 0x80000000, v3
	v_mov_b32_e32 v7, v2
	v_pk_mul_f32 v[6:7], v[0:1], v[6:7] op_sel_hi:[0,1]
	v_pk_fma_f32 v[2:3], v[84:85], v[2:3], v[6:7] op_sel_hi:[0,1,1]
	s_waitcnt lgkmcnt(7)
	v_pk_add_f32 v[2:3], v[148:149], v[2:3]
	ds_write2st64_b32 v104, v2, v3 offset0:24 offset1:25
	v_xor_b32_e32 v6, 0x80000000, v3
	v_mov_b32_e32 v7, v2
	v_pk_mul_f32 v[6:7], v[0:1], v[6:7] op_sel_hi:[0,1]
	v_pk_fma_f32 v[2:3], v[84:85], v[2:3], v[6:7] op_sel_hi:[0,1,1]
	s_waitcnt lgkmcnt(7)
	v_pk_add_f32 v[2:3], v[150:151], v[2:3]
	ds_write2st64_b32 v105, v2, v3 offset0:26 offset1:27
	v_xor_b32_e32 v6, 0x80000000, v3
	v_mov_b32_e32 v7, v2
	v_pk_mul_f32 v[6:7], v[0:1], v[6:7] op_sel_hi:[0,1]
	v_pk_fma_f32 v[2:3], v[84:85], v[2:3], v[6:7] op_sel_hi:[0,1,1]
	s_waitcnt lgkmcnt(7)
	v_pk_add_f32 v[2:3], v[152:153], v[2:3]
	ds_write2st64_b32 v106, v2, v3 offset0:28 offset1:29
	v_xor_b32_e32 v6, 0x80000000, v3
	v_mov_b32_e32 v7, v2
	v_pk_mul_f32 v[6:7], v[0:1], v[6:7] op_sel_hi:[0,1]
	v_pk_fma_f32 v[2:3], v[84:85], v[2:3], v[6:7] op_sel_hi:[0,1,1]
	s_waitcnt lgkmcnt(7)
	v_pk_add_f32 v[2:3], v[154:155], v[2:3]
	ds_write2st64_b32 v107, v2, v3 offset0:30 offset1:31
	s_waitcnt lgkmcnt(0)
	v_or_b32_e32 v216, 48, v82
	v_mov_b32_e32 v217, v83
	v_lshlrev_b64 v[216:217], 9, v[216:217]
	v_lshl_add_u64 v[216:217], v[216:217], 0, v[50:51]
	v_lshlrev_b64 v[216:217], 1, v[216:217]
	v_lshl_add_u64 v[216:217], s[8:9], 0, v[216:217]
	global_load_ushort v212, v[216:217], off
	global_load_ushort v213, v[216:217], off offset:1024
	global_load_ushort v214, v[216:217], off offset:2048
	global_load_ushort v215, v[216:217], off offset:3072
	ds_read_b128 v[2:5], v89
	ds_read_b128 v[6:9], v89 offset:16
	ds_read_b128 v[10:13], v89 offset:32
	ds_read_b128 v[14:17], v89 offset:48
	s_waitcnt lgkmcnt(3)
	v_mfma_f32_16x16x4_f32 v[18:21], v2, v97, 0
	v_mfma_f32_16x16x4_f32 v[22:25], v3, v96, 0
	v_mfma_f32_16x16x4_f32 v[18:21], v4, v95, v[18:21]
	v_mfma_f32_16x16x4_f32 v[2:5], v5, v94, v[22:25]
	s_waitcnt lgkmcnt(2)
	v_mfma_f32_16x16x4_f32 v[18:21], v6, v93, v[18:21]
	v_mfma_f32_16x16x4_f32 v[2:5], v7, v92, v[2:5]
	v_mfma_f32_16x16x4_f32 v[18:21], v8, v91, v[18:21]
	v_mfma_f32_16x16x4_f32 v[2:5], v9, v88, v[2:5]
	s_waitcnt lgkmcnt(1)
	v_mfma_f32_16x16x4_f32 v[6:9], v10, v85, v[18:21]
	v_mfma_f32_16x16x4_f32 v[2:5], v11, v55, v[2:5]
	v_mfma_f32_16x16x4_f32 v[6:9], v12, v56, v[6:9]
	v_mfma_f32_16x16x4_f32 v[2:5], v13, v57, v[2:5]
	ds_read_b128 v[10:13], v89 offset:64
	s_waitcnt lgkmcnt(1)
	v_mfma_f32_16x16x4_f32 v[6:9], v14, v58, v[6:9]
	v_mfma_f32_16x16x4_f32 v[2:5], v15, v59, v[2:5]
	v_mfma_f32_16x16x4_f32 v[6:9], v16, v60, v[6:9]
	v_mfma_f32_16x16x4_f32 v[2:5], v17, v61, v[2:5]
	s_waitcnt lgkmcnt(0)
	v_mfma_f32_16x16x4_f32 v[6:9], v10, v62, v[6:9]
	v_mfma_f32_16x16x4_f32 v[2:5], v11, v63, v[2:5]
	v_mfma_f32_16x16x4_f32 v[6:9], v12, v64, v[6:9]
	v_mfma_f32_16x16x4_f32 v[2:5], v13, v65, v[2:5]
	ds_read_b128 v[10:13], v89 offset:80
	s_waitcnt lgkmcnt(0)
	v_mfma_f32_16x16x4_f32 v[6:9], v10, v66, v[6:9]
	v_mfma_f32_16x16x4_f32 v[2:5], v11, v67, v[2:5]
	v_mfma_f32_16x16x4_f32 v[6:9], v12, v68, v[6:9]
	v_mfma_f32_16x16x4_f32 v[2:5], v13, v69, v[2:5]
	ds_read_b128 v[10:13], v89 offset:96
	s_waitcnt lgkmcnt(0)
; __device__ __forceinline__ float bf2f(bf16_t v) { return __uint_as_float(((unsigned)v) << 16); }
; __device__ __forceinline__ bf16_t f2bf(float f) { unsigned u = __float_as_uint(f); u += 0x7FFFu + ((u >> 16) & 1u); return (bf16_t)(u >> 16); }
; __device__ __forceinline__ void s5_pass2_item(PP p, unsigned char* shm, int item, int l) {
;     ...
;         for (int i = 0; i < 8; ++i) { const f32x4 xv = xrow[i];
;             y0 = __builtin_amdgcn_mfma_f32_16x16x4f32(xv[0], cmr[4 * i + 0], y0, 0, 0, 0);
;             y1 = __builtin_amdgcn_mfma_f32_16x16x4f32(xv[1], cmr[4 * i + 1], y1, 0, 0, 0);
;             y0 = __builtin_amdgcn_mfma_f32_16x16x4f32(xv[2], cmr[4 * i + 2], y0, 0, 0, 0);
;             y1 = __builtin_amdgcn_mfma_f32_16x16x4f32(xv[3], cmr[4 * i + 3], y1, 0, 0, 0); }
;         const f32x4 y = y0 + y1;
; #pragma unroll
;         for (int r = 0; r < 4; ++r) { const int tl = sc * 16 + quad * 4 + r;
;             const float v = y[r] + dsk * bf2f(proj[PJ_UA + (row0 + tl) * 512 + g * 16 + cc]);
;             const float z = 0.7978845608028654f * (v + 0.044715f * v * v * v);
;             const float th = 1.0f - 2.0f / (__expf(2.0f * z) + 1.0f);
;             Gout[(row0 + tl) * 512 + g * 16 + cc] = f2bf(0.5f * v * (1.0f + th)); }
;         __syncthreads();
;     }
	v_mfma_f32_16x16x4_f32 v[6:9], v10, v70, v[6:9]
	v_mfma_f32_16x16x4_f32 v[2:5], v11, v71, v[2:5]
	v_mfma_f32_16x16x4_f32 v[6:9], v12, v72, v[6:9]
	v_mfma_f32_16x16x4_f32 v[2:5], v13, v73, v[2:5]
	ds_read_b128 v[10:13], v89 offset:112
	s_waitcnt lgkmcnt(0)
	v_mfma_f32_16x16x4_f32 v[6:9], v10, v74, v[6:9]
	v_mfma_f32_16x16x4_f32 v[2:5], v11, v75, v[2:5]
	v_mfma_f32_16x16x4_f32 v[6:9], v12, v76, v[6:9]
	v_mfma_f32_16x16x4_f32 v[10:13], v13, v77, v[2:5]
	s_nop 9
	v_pk_add_f32 v[4:5], v[6:7], v[10:11]
	v_or_b32_e32 v6, 48, v82
	v_mov_b32_e32 v7, v83
	v_lshlrev_b64 v[6:7], 9, v[6:7]
	v_lshl_add_u64 v[6:7], v[6:7], 0, v[50:51]
	v_lshlrev_b64 v[6:7], 1, v[6:7]
	v_pk_add_f32 v[2:3], v[8:9], v[12:13]
	v_lshl_add_u64 v[8:9], s[8:9], 0, v[6:7]
	v_lshl_add_u64 v[6:7], s[28:29], 0, v[6:7]
	s_waitcnt vmcnt(3)
	v_lshlrev_b32_e32 v0, 16, v212
	v_fma_f32 v0, v54, v0, v4
	v_mul_f32_e32 v4, 0x3d372713, v0
	v_mul_f32_e32 v4, v0, v4
	v_fma_f32 v4, v0, v4, v0
	v_mul_f32_e32 v4, 0x3f4c422a, v4
	v_add_f32_e32 v4, v4, v4
	v_mul_f32_e32 v4, 0x3fb8aa3b, v4
	v_exp_f32_e32 v4, v4
	v_mul_f32_e32 v0, 0.5, v0
	v_add_f32_e32 v4, 1.0, v4
	v_div_scale_f32 v8, s[2:3], v4, v4, 2.0
	v_rcp_f32_e32 v9, v8
	s_nop 0
	v_fma_f32 v10, -v8, v9, 1.0
	v_fmac_f32_e32 v9, v10, v9
	v_div_scale_f32 v10, vcc, 2.0, v4, 2.0
	v_mul_f32_e32 v11, v10, v9
	v_fma_f32 v12, -v8, v11, v10
	v_fmac_f32_e32 v11, v12, v9
	v_fma_f32 v8, -v8, v11, v10
	v_div_fmas_f32 v8, v8, v9, v11
	v_div_fixup_f32 v4, v8, v4, 2.0
	v_sub_f32_e32 v4, 1.0, v4
	v_add_f32_e32 v4, 1.0, v4
	v_mul_f32_e32 v0, v0, v4
	v_bfe_u32 v4, v0, 16, 1
	v_add3_u32 v0, v0, v4, s31
	global_store_short_d16_hi v[6:7], v0, off
	v_or_b32_e32 v6, 49, v82
	v_mov_b32_e32 v7, v83
	v_lshlrev_b64 v[6:7], 9, v[6:7]
	v_lshl_add_u64 v[6:7], v[6:7], 0, v[50:51]
	v_lshlrev_b64 v[6:7], 1, v[6:7]
	v_lshl_add_u64 v[8:9], s[8:9], 0, v[6:7]
	s_waitcnt vmcnt(3)
	v_lshlrev_b32_e32 v0, 16, v213
	v_fmac_f32_e32 v5, v54, v0
	v_mul_f32_e32 v0, 0x3d372713, v5
	v_mul_f32_e32 v0, v5, v0
	v_fma_f32 v0, v5, v0, v5
	v_mul_f32_e32 v0, 0x3f4c422a, v0
	v_add_f32_e32 v0, v0, v0
	v_mul_f32_e32 v0, 0x3fb8aa3b, v0
	v_exp_f32_e32 v0, v0
	s_nop 0
	v_add_f32_e32 v0, 1.0, v0
	v_div_scale_f32 v4, s[2:3], v0, v0, 2.0
	v_rcp_f32_e32 v8, v4
	s_nop 0
	v_fma_f32 v9, -v4, v8, 1.0
	v_fmac_f32_e32 v8, v9, v8
	v_div_scale_f32 v9, vcc, 2.0, v0, 2.0
	v_mul_f32_e32 v10, v9, v8
	v_fma_f32 v11, -v4, v10, v9
	v_fmac_f32_e32 v10, v11, v8
	v_fma_f32 v4, -v4, v10, v9
	v_div_fmas_f32 v4, v4, v8, v10
	v_div_fixup_f32 v0, v4, v0, 2.0
	v_sub_f32_e32 v0, 1.0, v0
	v_mul_f32_e32 v4, 0.5, v5
	v_add_f32_e32 v0, 1.0, v0
	v_mul_f32_e32 v0, v4, v0
	v_bfe_u32 v4, v0, 16, 1
	v_add3_u32 v0, v0, v4, s31
	v_lshl_add_u64 v[4:5], s[28:29], 0, v[6:7]
	global_store_short_d16_hi v[4:5], v0, off
	v_or_b32_e32 v4, 50, v82
	v_mov_b32_e32 v5, v83
	v_lshlrev_b64 v[4:5], 9, v[4:5]
	v_lshl_add_u64 v[4:5], v[4:5], 0, v[50:51]
	v_lshlrev_b64 v[4:5], 1, v[4:5]
	v_lshl_add_u64 v[6:7], s[8:9], 0, v[4:5]
	v_lshl_add_u64 v[4:5], s[28:29], 0, v[4:5]
	v_or_b32_e32 v82, 51, v82
	s_waitcnt vmcnt(3)
	v_lshlrev_b32_e32 v0, 16, v214
	v_fma_f32 v0, v54, v0, v2
	v_mul_f32_e32 v2, 0x3d372713, v0
	v_mul_f32_e32 v2, v0, v2
	v_fma_f32 v2, v0, v2, v0
	v_mul_f32_e32 v2, 0x3f4c422a, v2
	v_add_f32_e32 v2, v2, v2
	v_mul_f32_e32 v2, 0x3fb8aa3b, v2
	v_exp_f32_e32 v2, v2
	v_mul_f32_e32 v0, 0.5, v0
	v_add_f32_e32 v2, 1.0, v2
	v_div_scale_f32 v6, s[2:3], v2, v2, 2.0
	v_rcp_f32_e32 v7, v6
	s_nop 0
	v_fma_f32 v8, -v6, v7, 1.0
	v_fmac_f32_e32 v7, v8, v7
	v_div_scale_f32 v8, vcc, 2.0, v2, 2.0
	v_mul_f32_e32 v9, v8, v7
	v_fma_f32 v10, -v6, v9, v8
	v_fmac_f32_e32 v9, v10, v7
	v_fma_f32 v6, -v6, v9, v8
	v_div_fmas_f32 v6, v6, v7, v9
	v_div_fixup_f32 v2, v6, v2, 2.0
	v_sub_f32_e32 v2, 1.0, v2
	v_add_f32_e32 v2, 1.0, v2
	v_mul_f32_e32 v0, v0, v2
	v_bfe_u32 v2, v0, 16, 1
	v_add3_u32 v0, v0, v2, s31
	global_store_short_d16_hi v[4:5], v0, off
	v_lshlrev_b64 v[4:5], 9, v[82:83]
	v_lshl_add_u64 v[4:5], v[4:5], 0, v[50:51]
	v_lshlrev_b64 v[4:5], 1, v[4:5]
	v_lshl_add_u64 v[6:7], s[8:9], 0, v[4:5]
	s_waitcnt vmcnt(3)
	v_lshlrev_b32_e32 v0, 16, v215
	v_fmac_f32_e32 v3, v54, v0
	v_mul_f32_e32 v0, 0x3d372713, v3
	v_mul_f32_e32 v0, v3, v0
	v_fma_f32 v0, v3, v0, v3
	v_mul_f32_e32 v0, 0x3f4c422a, v0
	v_add_f32_e32 v0, v0, v0
	v_mul_f32_e32 v0, 0x3fb8aa3b, v0
	v_exp_f32_e32 v0, v0
	s_nop 0
	v_add_f32_e32 v0, 1.0, v0
	v_div_scale_f32 v2, s[2:3], v0, v0, 2.0
	v_rcp_f32_e32 v6, v2
	s_nop 0
	v_fma_f32 v7, -v2, v6, 1.0
	v_fmac_f32_e32 v6, v7, v6
	v_div_scale_f32 v7, vcc, 2.0, v0, 2.0
	v_mul_f32_e32 v8, v7, v6
	v_fma_f32 v9, -v2, v8, v7
	v_fmac_f32_e32 v8, v9, v6
	v_fma_f32 v2, -v2, v8, v7
	v_div_fmas_f32 v2, v2, v6, v8
	v_div_fixup_f32 v0, v2, v0, 2.0
	v_sub_f32_e32 v0, 1.0, v0
	v_mul_f32_e32 v2, 0.5, v3
	v_add_f32_e32 v0, 1.0, v0
	v_mul_f32_e32 v0, v2, v0
	v_bfe_u32 v2, v0, 16, 1
	v_add3_u32 v0, v0, v2, s31
	v_lshl_add_u64 v[2:3], s[28:29], 0, v[4:5]
	global_store_short_d16_hi v[2:3], v0, off
	s_barrier
	s_cbranch_scc1 .LBB0_718
